# attention: waves 4-7 defer PV of fully visible key tiles to the next iteration (PV,QK,softmax order); V tile staging as 3-slot ring
# speedup vs baseline: 1.0030x; 1.0030x over previous
; DI float bf2f(short v) { return __uint_as_float(((unsigned)(unsigned short)v) << 16); }
; DI int opaque_tid512() { int t = threadIdx.x; asm volatile("" : "+v"(t)); return t; }
; DI void attn_phase(const bf16_t* __restrict__ qraw, const bf16_t* __restrict__ kbuf, const bf16_t* __restrict__ vtb, bf16_t* __restrict__ obuf,
;                    const float* __restrict__ gq, const float* __restrict__ cosT, const float* __restrict__ sinT, bf16_t* sm, int x, int j) {
;     ...
;     for (int half = 0; half < 2; ++half) {
;       const int tid = opaque_tid512(), lane = tid & 63, wave = tid >> 6, r = lane & 31, h = lane >> 5;
;       const int qb = half ? (p & 31) : (63 - (p & 31));
;       const int q0 = qb * 256 + wave * 32;
;       const size_t tok = (size_t)b * S + q0 + r;
;       bf16x8 qf[12];
;       {
;         const bf16_t* qp = qraw + tok * 1536 + hd * QKH + h * 8;
; #pragma unroll
;         for (int st = 0; st < 12; ++st) qf[st] = __builtin_nontemporal_load((const bf16x8*)(qp + st * 16));
;         float ss = 0.f;
; #pragma unroll
;         for (int st = 0; st < 12; ++st) {
; #pragma unroll
;           for (int e = 0; e < 8; ++e) { const float f = bf2f(qf[st][e]); ss += f * f; }
.LBB0_1280:
	s_xor_b64 s[56:57], s[0:1], -1
	v_mov_b32_e32 v53, v211
	s_and_b64 s[0:1], s[0:1], exec
	s_cselect_b32 s0, s87, s81
	v_ashrrev_i32_e32 v0, 1, v53
	s_lshl_b32 s0, s0, 8
	v_and_b32_e32 v0, 0xffffffe0, v0
	v_add_u32_e32 v186, s0, v0
	v_ashrrev_i32_e32 v187, 31, v186
	v_and_b32_e32 v51, 31, v53
	v_lshl_add_u64 v[184:185], s[10:11], 0, v[186:187]
	v_or_b32_e32 v184, v184, v51
	v_mov_b64_e32 v[2:3], s[12:13]
	v_bfe_u32 v52, v53, 5, 1
	v_mad_u64_u32 v[2:3], s[2:3], v184, s64, v[2:3]
	v_mad_i32_i24 v3, v185, s64, v3
	v_lshlrev_b32_e32 v0, 4, v52
	v_lshl_add_u64 v[2:3], v[2:3], 0, v[0:1]
	global_load_dwordx4 v[46:49], v[2:3], off nt
	global_load_dwordx4 v[42:45], v[2:3], off offset:32 nt
	global_load_dwordx4 v[38:41], v[2:3], off offset:64 nt
	global_load_dwordx4 v[34:37], v[2:3], off offset:96 nt
	global_load_dwordx4 v[30:33], v[2:3], off offset:128 nt
	global_load_dwordx4 v[26:29], v[2:3], off offset:160 nt
	global_load_dwordx4 v[22:25], v[2:3], off offset:192 nt
	global_load_dwordx4 v[18:21], v[2:3], off offset:224 nt
	global_load_dwordx4 v[14:17], v[2:3], off offset:256 nt
	global_load_dwordx4 v[6:9], v[2:3], off offset:288 nt
	global_load_dwordx4 v[10:13], v[2:3], off offset:320 nt
	s_nop 0
	global_load_dwordx4 v[2:5], v[2:3], off offset:352 nt
	s_mov_b32 s92, 1
	v_lshlrev_b32_e32 v187, 3, v52
	s_mov_b32 s31, 0
	s_waitcnt vmcnt(11)
	v_and_b32_e32 v0, 0xffff0000, v46
	v_lshlrev_b32_e32 v50, 16, v46
	v_mul_f32_e32 v0, v0, v0
	v_fmac_f32_e32 v0, v50, v50
	v_lshlrev_b32_e32 v50, 16, v47
	v_fmac_f32_e32 v0, v50, v50
	v_and_b32_e32 v50, 0xffff0000, v47
	v_fmac_f32_e32 v0, v50, v50
	v_lshlrev_b32_e32 v50, 16, v48
	v_fmac_f32_e32 v0, v50, v50
	v_and_b32_e32 v50, 0xffff0000, v48
	v_fmac_f32_e32 v0, v50, v50
	v_lshlrev_b32_e32 v50, 16, v49
	v_fmac_f32_e32 v0, v50, v50
	v_and_b32_e32 v50, 0xffff0000, v49
	v_fmac_f32_e32 v0, v50, v50
	s_waitcnt vmcnt(10)
	v_lshlrev_b32_e32 v50, 16, v42
	v_fmac_f32_e32 v0, v50, v50
	v_and_b32_e32 v50, 0xffff0000, v42
	v_fmac_f32_e32 v0, v50, v50
	v_lshlrev_b32_e32 v50, 16, v43
	v_fmac_f32_e32 v0, v50, v50
	v_and_b32_e32 v50, 0xffff0000, v43
	v_fmac_f32_e32 v0, v50, v50
	v_lshlrev_b32_e32 v50, 16, v44
	v_fmac_f32_e32 v0, v50, v50
	v_and_b32_e32 v50, 0xffff0000, v44
	v_fmac_f32_e32 v0, v50, v50
	v_lshlrev_b32_e32 v50, 16, v45
	v_fmac_f32_e32 v0, v50, v50
	v_and_b32_e32 v50, 0xffff0000, v45
	v_fmac_f32_e32 v0, v50, v50
	s_waitcnt vmcnt(9)
	v_lshlrev_b32_e32 v50, 16, v38
	v_fmac_f32_e32 v0, v50, v50
	v_and_b32_e32 v50, 0xffff0000, v38
	v_fmac_f32_e32 v0, v50, v50
	v_lshlrev_b32_e32 v50, 16, v39
	v_fmac_f32_e32 v0, v50, v50
	v_and_b32_e32 v50, 0xffff0000, v39
	v_fmac_f32_e32 v0, v50, v50
	v_lshlrev_b32_e32 v50, 16, v40
	v_fmac_f32_e32 v0, v50, v50
	v_and_b32_e32 v50, 0xffff0000, v40
	v_fmac_f32_e32 v0, v50, v50
	v_lshlrev_b32_e32 v50, 16, v41
	v_fmac_f32_e32 v0, v50, v50
	v_and_b32_e32 v50, 0xffff0000, v41
	v_fmac_f32_e32 v0, v50, v50
	s_waitcnt vmcnt(8)
	v_lshlrev_b32_e32 v50, 16, v34
	v_fmac_f32_e32 v0, v50, v50
	v_and_b32_e32 v50, 0xffff0000, v34
	v_fmac_f32_e32 v0, v50, v50
	v_lshlrev_b32_e32 v50, 16, v35
	v_fmac_f32_e32 v0, v50, v50
	v_and_b32_e32 v50, 0xffff0000, v35
	v_fmac_f32_e32 v0, v50, v50
	v_lshlrev_b32_e32 v50, 16, v36
	v_fmac_f32_e32 v0, v50, v50
	v_and_b32_e32 v50, 0xffff0000, v36
	v_fmac_f32_e32 v0, v50, v50
	v_lshlrev_b32_e32 v50, 16, v37
	v_fmac_f32_e32 v0, v50, v50
	v_and_b32_e32 v50, 0xffff0000, v37
	v_fmac_f32_e32 v0, v50, v50
	s_waitcnt vmcnt(7)
	v_lshlrev_b32_e32 v50, 16, v30
	v_fmac_f32_e32 v0, v50, v50
	v_and_b32_e32 v50, 0xffff0000, v30
	v_fmac_f32_e32 v0, v50, v50
	v_lshlrev_b32_e32 v50, 16, v31
	v_fmac_f32_e32 v0, v50, v50
	v_and_b32_e32 v50, 0xffff0000, v31
	v_fmac_f32_e32 v0, v50, v50
	v_lshlrev_b32_e32 v50, 16, v32
	v_fmac_f32_e32 v0, v50, v50
	v_and_b32_e32 v50, 0xffff0000, v32
	v_fmac_f32_e32 v0, v50, v50
	v_lshlrev_b32_e32 v50, 16, v33
	v_fmac_f32_e32 v0, v50, v50
	v_and_b32_e32 v50, 0xffff0000, v33
	v_fmac_f32_e32 v0, v50, v50
	s_waitcnt vmcnt(6)
	v_lshlrev_b32_e32 v50, 16, v26
	v_fmac_f32_e32 v0, v50, v50
	v_and_b32_e32 v50, 0xffff0000, v26
	v_fmac_f32_e32 v0, v50, v50
	v_lshlrev_b32_e32 v50, 16, v27
	v_fmac_f32_e32 v0, v50, v50
	v_and_b32_e32 v50, 0xffff0000, v27
	v_fmac_f32_e32 v0, v50, v50
	v_lshlrev_b32_e32 v50, 16, v28
	v_fmac_f32_e32 v0, v50, v50
	v_and_b32_e32 v50, 0xffff0000, v28
	v_fmac_f32_e32 v0, v50, v50
	v_lshlrev_b32_e32 v50, 16, v29
	v_fmac_f32_e32 v0, v50, v50
	v_and_b32_e32 v50, 0xffff0000, v29
	v_fmac_f32_e32 v0, v50, v50
	s_waitcnt vmcnt(5)
	v_lshlrev_b32_e32 v50, 16, v22
	v_fmac_f32_e32 v0, v50, v50
	v_and_b32_e32 v50, 0xffff0000, v22
	v_fmac_f32_e32 v0, v50, v50
	v_lshlrev_b32_e32 v50, 16, v23
	v_fmac_f32_e32 v0, v50, v50
	v_and_b32_e32 v50, 0xffff0000, v23
	v_fmac_f32_e32 v0, v50, v50
	v_lshlrev_b32_e32 v50, 16, v24
	v_fmac_f32_e32 v0, v50, v50
	v_and_b32_e32 v50, 0xffff0000, v24
	v_fmac_f32_e32 v0, v50, v50
	v_lshlrev_b32_e32 v50, 16, v25
	v_fmac_f32_e32 v0, v50, v50
	v_and_b32_e32 v50, 0xffff0000, v25
	v_fmac_f32_e32 v0, v50, v50
	s_waitcnt vmcnt(4)
	v_lshlrev_b32_e32 v50, 16, v18
	v_fmac_f32_e32 v0, v50, v50
	v_and_b32_e32 v50, 0xffff0000, v18
	v_fmac_f32_e32 v0, v50, v50
	v_lshlrev_b32_e32 v50, 16, v19
	v_fmac_f32_e32 v0, v50, v50
	v_and_b32_e32 v50, 0xffff0000, v19
	v_fmac_f32_e32 v0, v50, v50
	v_lshlrev_b32_e32 v50, 16, v20
	v_fmac_f32_e32 v0, v50, v50
	v_and_b32_e32 v50, 0xffff0000, v20
	v_fmac_f32_e32 v0, v50, v50
	v_lshlrev_b32_e32 v50, 16, v21
	v_fmac_f32_e32 v0, v50, v50
	v_and_b32_e32 v50, 0xffff0000, v21
	v_fmac_f32_e32 v0, v50, v50
	s_waitcnt vmcnt(3)
; DI unsigned pack_bf16(float lo, float hi) { f32x2 v = {lo, hi}; bf16v2 b = __builtin_convertvector(v, bf16v2); return __builtin_bit_cast(unsigned, b); }
; DI float bf2f(short v) { return __uint_as_float(((unsigned)(unsigned short)v) << 16); }
; DI void attn_phase(const bf16_t* __restrict__ qraw, const bf16_t* __restrict__ kbuf, const bf16_t* __restrict__ vtb, bf16_t* __restrict__ obuf,
;                    const float* __restrict__ gq, const float* __restrict__ cosT, const float* __restrict__ sinT, bf16_t* sm, int x, int j) {
;     ...
;         float ss = 0.f;
; #pragma unroll
;         for (int st = 0; st < 12; ++st) {
; #pragma unroll
;           for (int e = 0; e < 8; ++e) { const float f = bf2f(qf[st][e]); ss += f * f; }
;           u32x4 t = __builtin_bit_cast(u32x4, qf[st]);
;           asm volatile("" : "+v"(t));
;           qf[st] = __builtin_bit_cast(bf16x8, t);
;         }
;         ss += __shfl_xor(ss, 32);
;         const float rq = rsqrtf(ss * (1.f / QKH) + EPS) * (0.07216878364870322f * 1.4426950408889634f);
;         __builtin_amdgcn_sched_barrier(0);
; #pragma unroll
;         for (int st = 0; st < 8; ++st) {
;           const f32x4 ga = *(const f32x4*)(gq + st * 16 + h * 8), gb = *(const f32x4*)(gq + st * 16 + h * 8 + 4);
;           u32x4 o;
;           o.x = pack_bf16(bf2f(qf[st][0]) * rq * ga.x, bf2f(qf[st][1]) * rq * ga.y);
;           o.y = pack_bf16(bf2f(qf[st][2]) * rq * ga.z, bf2f(qf[st][3]) * rq * ga.w);
;           o.z = pack_bf16(bf2f(qf[st][4]) * rq * gb.x, bf2f(qf[st][5]) * rq * gb.y);
;           o.w = pack_bf16(bf2f(qf[st][6]) * rq * gb.z, bf2f(qf[st][7]) * rq * gb.w);
;           asm volatile("" : "+v"(o));
;           qf[st] = __builtin_bit_cast(bf16x8, o);
;           __builtin_amdgcn_sched_barrier(0);
;         }
	v_lshlrev_b32_e32 v50, 16, v14
	v_fmac_f32_e32 v0, v50, v50
	v_and_b32_e32 v50, 0xffff0000, v14
	v_fmac_f32_e32 v0, v50, v50
	v_lshlrev_b32_e32 v50, 16, v15
	v_fmac_f32_e32 v0, v50, v50
	v_and_b32_e32 v50, 0xffff0000, v15
	v_fmac_f32_e32 v0, v50, v50
	v_lshlrev_b32_e32 v50, 16, v16
	v_fmac_f32_e32 v0, v50, v50
	v_and_b32_e32 v50, 0xffff0000, v16
	v_fmac_f32_e32 v0, v50, v50
	v_lshlrev_b32_e32 v50, 16, v17
	v_fmac_f32_e32 v0, v50, v50
	v_and_b32_e32 v50, 0xffff0000, v17
	v_fmac_f32_e32 v0, v50, v50
	s_waitcnt vmcnt(2)
	v_lshlrev_b32_e32 v50, 16, v6
	v_fmac_f32_e32 v0, v50, v50
	v_and_b32_e32 v50, 0xffff0000, v6
	v_fmac_f32_e32 v0, v50, v50
	v_lshlrev_b32_e32 v50, 16, v7
	v_fmac_f32_e32 v0, v50, v50
	v_and_b32_e32 v50, 0xffff0000, v7
	v_fmac_f32_e32 v0, v50, v50
	v_lshlrev_b32_e32 v50, 16, v8
	v_fmac_f32_e32 v0, v50, v50
	v_and_b32_e32 v50, 0xffff0000, v8
	v_fmac_f32_e32 v0, v50, v50
	v_lshlrev_b32_e32 v50, 16, v9
	v_fmac_f32_e32 v0, v50, v50
	v_and_b32_e32 v50, 0xffff0000, v9
	v_fmac_f32_e32 v0, v50, v50
	s_waitcnt vmcnt(1)
	v_lshlrev_b32_e32 v50, 16, v10
	v_fmac_f32_e32 v0, v50, v50
	v_and_b32_e32 v50, 0xffff0000, v10
	v_fmac_f32_e32 v0, v50, v50
	v_lshlrev_b32_e32 v50, 16, v11
	v_fmac_f32_e32 v0, v50, v50
	v_and_b32_e32 v50, 0xffff0000, v11
	v_fmac_f32_e32 v0, v50, v50
	v_lshlrev_b32_e32 v50, 16, v12
	v_fmac_f32_e32 v0, v50, v50
	v_and_b32_e32 v50, 0xffff0000, v12
	v_and_b32_e32 v55, 0xffff0000, v13
	v_lshlrev_b32_e32 v54, 16, v13
	v_fmac_f32_e32 v0, v50, v50
	v_pk_mul_f32 v[54:55], v[54:55], v[54:55]
	v_xor_b32_e32 v50, 32, v219
	v_add_f32_e32 v0, v54, v0
	v_add_f32_e32 v0, v55, v0
	s_waitcnt vmcnt(0)
	v_and_b32_e32 v55, 0xffff0000, v2
	v_lshlrev_b32_e32 v54, 16, v2
	v_pk_mul_f32 v[54:55], v[54:55], v[54:55]
	s_nop 0
	v_add_f32_e32 v0, v54, v0
	v_add_f32_e32 v0, v55, v0
	v_and_b32_e32 v55, 0xffff0000, v3
	v_lshlrev_b32_e32 v54, 16, v3
	v_pk_mul_f32 v[54:55], v[54:55], v[54:55]
	s_nop 0
	v_add_f32_e32 v0, v54, v0
	v_add_f32_e32 v0, v55, v0
	v_and_b32_e32 v55, 0xffff0000, v4
	v_lshlrev_b32_e32 v54, 16, v4
	v_pk_mul_f32 v[54:55], v[54:55], v[54:55]
	s_nop 0
	v_add_f32_e32 v0, v54, v0
	v_add_f32_e32 v0, v55, v0
	v_and_b32_e32 v55, 0xffff0000, v5
	v_lshlrev_b32_e32 v54, 16, v5
	v_pk_mul_f32 v[54:55], v[54:55], v[54:55]
	s_nop 0
	v_add_f32_e32 v0, v54, v0
	v_and_b32_e32 v54, 64, v219
	v_add_u32_e32 v54, 64, v54
	v_cmp_lt_i32_e32 vcc, v50, v54
	v_add_f32_e32 v0, v55, v0
	s_nop 0
	v_cndmask_b32_e32 v50, v219, v50, vcc
	v_lshlrev_b32_e32 v50, 2, v50
	ds_bpermute_b32 v50, v50, v0
	s_waitcnt lgkmcnt(0)
	v_add_f32_e32 v0, v0, v50
	v_fmamk_f32 v0, v0, 0x3baaaaab, v210
	v_cmp_gt_f32_e32 vcc, s29, v0
	v_mul_f32_e32 v50, 0x4b800000, v0
	s_nop 0
	v_cndmask_b32_e32 v0, v0, v50, vcc
	v_rsq_f32_e32 v0, v0
	s_nop 0
	v_mul_f32_e32 v50, 0x45800000, v0
	v_cndmask_b32_e32 v0, v0, v50, vcc
	v_mul_f32_e32 v50, 0x3dd53b94, v0
	v_lshlrev_b32_e32 v0, 5, v52
	global_load_dwordx4 v[54:57], v0, s[8:9] offset:16
	global_load_dwordx4 v[58:61], v0, s[8:9]
	v_and_b32_e32 v63, 0xffff0000, v46
	v_lshlrev_b32_e32 v62, 16, v46
	v_pk_mul_f32 v[62:63], v[50:51], v[62:63] op_sel_hi:[0,1]
	s_waitcnt vmcnt(0)
	v_pk_mul_f32 v[58:59], v[58:59], v[62:63]
	s_nop 0
	v_cvt_pk_bf16_f32 v112, v58, v59
	v_and_b32_e32 v59, 0xffff0000, v47
	v_lshlrev_b32_e32 v58, 16, v47
	v_pk_mul_f32 v[46:47], v[50:51], v[58:59] op_sel_hi:[0,1]
	v_pk_mul_f32 v[46:47], v[60:61], v[46:47]
	s_nop 0
	v_cvt_pk_bf16_f32 v113, v46, v47
	v_and_b32_e32 v47, 0xffff0000, v48
	v_lshlrev_b32_e32 v46, 16, v48
	v_pk_mul_f32 v[46:47], v[50:51], v[46:47] op_sel_hi:[0,1]
	v_pk_mul_f32 v[46:47], v[54:55], v[46:47]
	s_nop 0
	v_cvt_pk_bf16_f32 v114, v46, v47
	v_and_b32_e32 v47, 0xffff0000, v49
	v_lshlrev_b32_e32 v46, 16, v49
	v_pk_mul_f32 v[46:47], v[50:51], v[46:47] op_sel_hi:[0,1]
	v_pk_mul_f32 v[46:47], v[56:57], v[46:47]
	s_nop 0
	v_cvt_pk_bf16_f32 v115, v46, v47
	global_load_dwordx4 v[46:49], v0, s[8:9] offset:80
	global_load_dwordx4 v[54:57], v0, s[8:9] offset:64
	v_and_b32_e32 v59, 0xffff0000, v42
	v_lshlrev_b32_e32 v58, 16, v42
	v_pk_mul_f32 v[58:59], v[50:51], v[58:59] op_sel_hi:[0,1]
	s_waitcnt vmcnt(0)
	v_pk_mul_f32 v[54:55], v[54:55], v[58:59]
	s_nop 0
	v_cvt_pk_bf16_f32 v116, v54, v55
	v_and_b32_e32 v55, 0xffff0000, v43
	v_lshlrev_b32_e32 v54, 16, v43
	v_pk_mul_f32 v[42:43], v[50:51], v[54:55] op_sel_hi:[0,1]
	v_pk_mul_f32 v[42:43], v[56:57], v[42:43]
	s_nop 0
	v_cvt_pk_bf16_f32 v117, v42, v43
	v_and_b32_e32 v43, 0xffff0000, v44
	v_lshlrev_b32_e32 v42, 16, v44
	v_pk_mul_f32 v[42:43], v[50:51], v[42:43] op_sel_hi:[0,1]
	v_pk_mul_f32 v[42:43], v[46:47], v[42:43]
	s_nop 0
	v_cvt_pk_bf16_f32 v118, v42, v43
	v_and_b32_e32 v43, 0xffff0000, v45
	v_lshlrev_b32_e32 v42, 16, v45
	v_pk_mul_f32 v[42:43], v[50:51], v[42:43] op_sel_hi:[0,1]
	v_pk_mul_f32 v[42:43], v[48:49], v[42:43]
	s_nop 0
	v_cvt_pk_bf16_f32 v119, v42, v43
	global_load_dwordx4 v[42:45], v0, s[8:9] offset:144
	global_load_dwordx4 v[46:49], v0, s[8:9] offset:128
	v_and_b32_e32 v55, 0xffff0000, v38
	v_lshlrev_b32_e32 v54, 16, v38
	v_pk_mul_f32 v[54:55], v[50:51], v[54:55] op_sel_hi:[0,1]
	s_waitcnt vmcnt(0)
	v_pk_mul_f32 v[46:47], v[46:47], v[54:55]
	s_nop 0
	v_cvt_pk_bf16_f32 v120, v46, v47
	v_and_b32_e32 v47, 0xffff0000, v39
	v_lshlrev_b32_e32 v46, 16, v39
	v_pk_mul_f32 v[38:39], v[50:51], v[46:47] op_sel_hi:[0,1]
	v_pk_mul_f32 v[38:39], v[48:49], v[38:39]
	s_nop 0
	v_cvt_pk_bf16_f32 v121, v38, v39
	v_and_b32_e32 v39, 0xffff0000, v40
	v_lshlrev_b32_e32 v38, 16, v40
	v_pk_mul_f32 v[38:39], v[50:51], v[38:39] op_sel_hi:[0,1]
	v_pk_mul_f32 v[38:39], v[42:43], v[38:39]
	s_nop 0
	v_cvt_pk_bf16_f32 v122, v38, v39
	v_and_b32_e32 v39, 0xffff0000, v41
	v_lshlrev_b32_e32 v38, 16, v41
	v_pk_mul_f32 v[38:39], v[50:51], v[38:39] op_sel_hi:[0,1]
	v_pk_mul_f32 v[38:39], v[44:45], v[38:39]
	s_nop 0
	v_cvt_pk_bf16_f32 v123, v38, v39
	global_load_dwordx4 v[38:41], v0, s[8:9] offset:208
	global_load_dwordx4 v[42:45], v0, s[8:9] offset:192
	v_and_b32_e32 v47, 0xffff0000, v34
	v_lshlrev_b32_e32 v46, 16, v34
	v_pk_mul_f32 v[46:47], v[50:51], v[46:47] op_sel_hi:[0,1]
	s_waitcnt vmcnt(0)
; DI unsigned pack_bf16(float lo, float hi) { f32x2 v = {lo, hi}; bf16v2 b = __builtin_convertvector(v, bf16v2); return __builtin_bit_cast(unsigned, b); }
; DI float bf2f(short v) { return __uint_as_float(((unsigned)(unsigned short)v) << 16); }
; DI void attn_phase(const bf16_t* __restrict__ qraw, const bf16_t* __restrict__ kbuf, const bf16_t* __restrict__ vtb, bf16_t* __restrict__ obuf,
;                    const float* __restrict__ gq, const float* __restrict__ cosT, const float* __restrict__ sinT, bf16_t* sm, int x, int j) {
;     ...
;         for (int st = 0; st < 8; ++st) {
;           const f32x4 ga = *(const f32x4*)(gq + st * 16 + h * 8), gb = *(const f32x4*)(gq + st * 16 + h * 8 + 4);
;           u32x4 o;
;           o.x = pack_bf16(bf2f(qf[st][0]) * rq * ga.x, bf2f(qf[st][1]) * rq * ga.y);
;           o.y = pack_bf16(bf2f(qf[st][2]) * rq * ga.z, bf2f(qf[st][3]) * rq * ga.w);
;           o.z = pack_bf16(bf2f(qf[st][4]) * rq * gb.x, bf2f(qf[st][5]) * rq * gb.y);
;           o.w = pack_bf16(bf2f(qf[st][6]) * rq * gb.z, bf2f(qf[st][7]) * rq * gb.w);
;           asm volatile("" : "+v"(o));
;           qf[st] = __builtin_bit_cast(bf16x8, o);
;           __builtin_amdgcn_sched_barrier(0);
;         }
; #pragma unroll
;         for (int st = 8; st < 10; ++st) {
;           const int jb = (st - 8) * 16 + h * 8;
;           u32x4 o1, o2;
; #pragma unroll
;           for (int hf = 0; hf < 2; ++hf) {
;             const f32x4 g1 = *(const f32x4*)(gq + 128 + jb + 4 * hf), g2 = *(const f32x4*)(gq + 160 + jb + 4 * hf);
;             const f32x4 cc = *(const f32x4*)(cosT + tok * 32 + jb + 4 * hf), sn = *(const f32x4*)(sinT + tok * 32 + jb + 4 * hf);
;             float y1[4], y2[4];
; #pragma unroll
;             for (int e = 0; e < 4; ++e) {
;               const float x1 = bf2f(qf[st][4 * hf + e]) * rq * g1[e], x2 = bf2f(qf[st + 2][4 * hf + e]) * rq * g2[e];
;               y1[e] = x1 * cc[e] - x2 * sn[e]; y2[e] = x2 * cc[e] + x1 * sn[e];
	v_pk_mul_f32 v[42:43], v[42:43], v[46:47]
	s_nop 0
	v_cvt_pk_bf16_f32 v124, v42, v43
	v_and_b32_e32 v43, 0xffff0000, v35
	v_lshlrev_b32_e32 v42, 16, v35
	v_pk_mul_f32 v[34:35], v[50:51], v[42:43] op_sel_hi:[0,1]
	v_pk_mul_f32 v[34:35], v[44:45], v[34:35]
	s_nop 0
	v_cvt_pk_bf16_f32 v125, v34, v35
	v_and_b32_e32 v35, 0xffff0000, v36
	v_lshlrev_b32_e32 v34, 16, v36
	v_pk_mul_f32 v[34:35], v[50:51], v[34:35] op_sel_hi:[0,1]
	v_pk_mul_f32 v[34:35], v[38:39], v[34:35]
	s_nop 0
	v_cvt_pk_bf16_f32 v126, v34, v35
	v_and_b32_e32 v35, 0xffff0000, v37
	v_lshlrev_b32_e32 v34, 16, v37
	v_pk_mul_f32 v[34:35], v[50:51], v[34:35] op_sel_hi:[0,1]
	v_pk_mul_f32 v[34:35], v[40:41], v[34:35]
	s_nop 0
	v_cvt_pk_bf16_f32 v127, v34, v35
	global_load_dwordx4 v[34:37], v0, s[8:9] offset:272
	global_load_dwordx4 v[38:41], v0, s[8:9] offset:256
	v_and_b32_e32 v43, 0xffff0000, v30
	v_lshlrev_b32_e32 v42, 16, v30
	v_pk_mul_f32 v[42:43], v[50:51], v[42:43] op_sel_hi:[0,1]
	s_waitcnt vmcnt(0)
	v_pk_mul_f32 v[38:39], v[38:39], v[42:43]
	s_nop 0
	v_cvt_pk_bf16_f32 v128, v38, v39
	v_and_b32_e32 v39, 0xffff0000, v31
	v_lshlrev_b32_e32 v38, 16, v31
	v_pk_mul_f32 v[30:31], v[50:51], v[38:39] op_sel_hi:[0,1]
	v_pk_mul_f32 v[30:31], v[40:41], v[30:31]
	s_nop 0
	v_cvt_pk_bf16_f32 v129, v30, v31
	v_and_b32_e32 v31, 0xffff0000, v32
	v_lshlrev_b32_e32 v30, 16, v32
	v_pk_mul_f32 v[30:31], v[50:51], v[30:31] op_sel_hi:[0,1]
	v_pk_mul_f32 v[30:31], v[34:35], v[30:31]
	s_nop 0
	v_cvt_pk_bf16_f32 v130, v30, v31
	v_and_b32_e32 v31, 0xffff0000, v33
	v_lshlrev_b32_e32 v30, 16, v33
	v_pk_mul_f32 v[30:31], v[50:51], v[30:31] op_sel_hi:[0,1]
	v_pk_mul_f32 v[30:31], v[36:37], v[30:31]
	s_nop 0
	v_cvt_pk_bf16_f32 v131, v30, v31
	global_load_dwordx4 v[30:33], v0, s[8:9] offset:336
	global_load_dwordx4 v[34:37], v0, s[8:9] offset:320
	v_and_b32_e32 v39, 0xffff0000, v26
	v_lshlrev_b32_e32 v38, 16, v26
	v_pk_mul_f32 v[38:39], v[50:51], v[38:39] op_sel_hi:[0,1]
	s_waitcnt vmcnt(0)
	v_pk_mul_f32 v[34:35], v[34:35], v[38:39]
	s_nop 0
	v_cvt_pk_bf16_f32 v132, v34, v35
	v_and_b32_e32 v35, 0xffff0000, v27
	v_lshlrev_b32_e32 v34, 16, v27
	v_pk_mul_f32 v[26:27], v[50:51], v[34:35] op_sel_hi:[0,1]
	v_pk_mul_f32 v[26:27], v[36:37], v[26:27]
	s_nop 0
	v_cvt_pk_bf16_f32 v133, v26, v27
	v_and_b32_e32 v27, 0xffff0000, v28
	v_lshlrev_b32_e32 v26, 16, v28
	v_pk_mul_f32 v[26:27], v[50:51], v[26:27] op_sel_hi:[0,1]
	v_pk_mul_f32 v[26:27], v[30:31], v[26:27]
	s_nop 0
	v_cvt_pk_bf16_f32 v134, v26, v27
	v_and_b32_e32 v27, 0xffff0000, v29
	v_lshlrev_b32_e32 v26, 16, v29
	v_pk_mul_f32 v[26:27], v[50:51], v[26:27] op_sel_hi:[0,1]
	v_pk_mul_f32 v[26:27], v[32:33], v[26:27]
	s_nop 0
	v_cvt_pk_bf16_f32 v135, v26, v27
	global_load_dwordx4 v[26:29], v0, s[8:9] offset:400
	global_load_dwordx4 v[30:33], v0, s[8:9] offset:384
	v_and_b32_e32 v35, 0xffff0000, v22
	v_lshlrev_b32_e32 v34, 16, v22
	v_pk_mul_f32 v[34:35], v[50:51], v[34:35] op_sel_hi:[0,1]
	s_waitcnt vmcnt(0)
	v_pk_mul_f32 v[30:31], v[30:31], v[34:35]
	s_nop 0
	v_cvt_pk_bf16_f32 v136, v30, v31
	v_and_b32_e32 v31, 0xffff0000, v23
	v_lshlrev_b32_e32 v30, 16, v23
	v_pk_mul_f32 v[22:23], v[50:51], v[30:31] op_sel_hi:[0,1]
	v_pk_mul_f32 v[22:23], v[32:33], v[22:23]
	s_nop 0
	v_cvt_pk_bf16_f32 v137, v22, v23
	v_and_b32_e32 v23, 0xffff0000, v24
	v_lshlrev_b32_e32 v22, 16, v24
	v_pk_mul_f32 v[22:23], v[50:51], v[22:23] op_sel_hi:[0,1]
	v_pk_mul_f32 v[22:23], v[26:27], v[22:23]
	s_nop 0
	v_cvt_pk_bf16_f32 v138, v22, v23
	v_and_b32_e32 v23, 0xffff0000, v25
	v_lshlrev_b32_e32 v22, 16, v25
	v_pk_mul_f32 v[22:23], v[50:51], v[22:23] op_sel_hi:[0,1]
	v_pk_mul_f32 v[22:23], v[28:29], v[22:23]
	s_nop 0
	v_cvt_pk_bf16_f32 v139, v22, v23
	global_load_dwordx4 v[22:25], v0, s[8:9] offset:464
	global_load_dwordx4 v[26:29], v0, s[8:9] offset:448
	v_and_b32_e32 v31, 0xffff0000, v18
	v_lshlrev_b32_e32 v30, 16, v18
	v_pk_mul_f32 v[30:31], v[50:51], v[30:31] op_sel_hi:[0,1]
	s_waitcnt vmcnt(0)
	v_pk_mul_f32 v[26:27], v[26:27], v[30:31]
	s_nop 0
	v_cvt_pk_bf16_f32 v140, v26, v27
	v_and_b32_e32 v27, 0xffff0000, v19
	v_lshlrev_b32_e32 v26, 16, v19
	v_pk_mul_f32 v[18:19], v[50:51], v[26:27] op_sel_hi:[0,1]
	v_pk_mul_f32 v[18:19], v[28:29], v[18:19]
	s_nop 0
	v_cvt_pk_bf16_f32 v141, v18, v19
	v_and_b32_e32 v19, 0xffff0000, v20
	v_lshlrev_b32_e32 v18, 16, v20
	v_pk_mul_f32 v[18:19], v[50:51], v[18:19] op_sel_hi:[0,1]
	v_pk_mul_f32 v[18:19], v[22:23], v[18:19]
	s_nop 0
	v_cvt_pk_bf16_f32 v142, v18, v19
	v_and_b32_e32 v19, 0xffff0000, v21
	v_lshlrev_b32_e32 v18, 16, v21
	v_pk_mul_f32 v[18:19], v[50:51], v[18:19] op_sel_hi:[0,1]
	v_pk_mul_f32 v[18:19], v[24:25], v[18:19]
	s_nop 0
	v_cvt_pk_bf16_f32 v143, v18, v19
	v_lshlrev_b64 v[18:19], 7, v[184:185]
	v_lshl_add_u64 v[20:21], s[24:25], 0, v[18:19]
	v_lshl_add_u64 v[18:19], s[26:27], 0, v[18:19]
	v_lshl_add_u64 v[36:37], v[18:19], 0, v[0:1]
	v_lshl_add_u64 v[34:35], v[20:21], 0, v[0:1]
	global_load_dwordx4 v[18:21], v[36:37], off offset:16
	global_load_dwordx4 v[38:41], v[36:37], off
	global_load_dwordx4 v[30:33], v0, s[8:9] offset:528
	global_load_dwordx4 v[42:45], v0, s[8:9] offset:512
	global_load_dwordx4 v[22:25], v[34:35], off offset:16
	global_load_dwordx4 v[46:49], v[34:35], off
	global_load_dwordx4 v[26:29], v0, s[8:9] offset:656
	global_load_dwordx4 v[54:57], v0, s[8:9] offset:640
	v_and_b32_e32 v59, 0xffff0000, v15
	v_lshlrev_b32_e32 v58, 16, v15
	v_pk_mul_f32 v[58:59], v[50:51], v[58:59] op_sel_hi:[0,1]
	v_and_b32_e32 v15, 0xffff0000, v14
	v_lshlrev_b32_e32 v14, 16, v14
	v_pk_mul_f32 v[14:15], v[50:51], v[14:15] op_sel_hi:[0,1]
	s_waitcnt vmcnt(4)
; DI unsigned pack_bf16(float lo, float hi) { f32x2 v = {lo, hi}; bf16v2 b = __builtin_convertvector(v, bf16v2); return __builtin_bit_cast(unsigned, b); }
; DI float bf2f(short v) { return __uint_as_float(((unsigned)(unsigned short)v) << 16); }
; DI void attn_phase(const bf16_t* __restrict__ qraw, const bf16_t* __restrict__ kbuf, const bf16_t* __restrict__ vtb, bf16_t* __restrict__ obuf,
;                    const float* __restrict__ gq, const float* __restrict__ cosT, const float* __restrict__ sinT, bf16_t* sm, int x, int j) {
;     ...
;         for (int st = 8; st < 10; ++st) {
;           const int jb = (st - 8) * 16 + h * 8;
;           u32x4 o1, o2;
; #pragma unroll
;           for (int hf = 0; hf < 2; ++hf) {
;             const f32x4 g1 = *(const f32x4*)(gq + 128 + jb + 4 * hf), g2 = *(const f32x4*)(gq + 160 + jb + 4 * hf);
;             const f32x4 cc = *(const f32x4*)(cosT + tok * 32 + jb + 4 * hf), sn = *(const f32x4*)(sinT + tok * 32 + jb + 4 * hf);
;             float y1[4], y2[4];
; #pragma unroll
;             for (int e = 0; e < 4; ++e) {
;               const float x1 = bf2f(qf[st][4 * hf + e]) * rq * g1[e], x2 = bf2f(qf[st + 2][4 * hf + e]) * rq * g2[e];
;               y1[e] = x1 * cc[e] - x2 * sn[e]; y2[e] = x2 * cc[e] + x1 * sn[e];
;             }
;             if (hf == 0) { o1.x = pack_bf16(y1[0], y1[1]); o1.y = pack_bf16(y1[2], y1[3]); o2.x = pack_bf16(y2[0], y2[1]); o2.y = pack_bf16(y2[2], y2[3]); }
;             else { o1.z = pack_bf16(y1[0], y1[1]); o1.w = pack_bf16(y1[2], y1[3]); o2.z = pack_bf16(y2[0], y2[1]); o2.w = pack_bf16(y2[2], y2[3]); }
;           }
;           asm volatile("" : "+v"(o1), "+v"(o2));
;           qf[st] = __builtin_bit_cast(bf16x8, o1); qf[st + 2] = __builtin_bit_cast(bf16x8, o2);
	v_pk_mul_f32 v[44:45], v[44:45], v[58:59]
	v_and_b32_e32 v59, 0xffff0000, v11
	v_lshlrev_b32_e32 v58, 16, v11
	v_and_b32_e32 v11, 0xffff0000, v10
	v_lshlrev_b32_e32 v10, 16, v10
	v_pk_mul_f32 v[10:11], v[50:51], v[10:11] op_sel_hi:[0,1]
	s_waitcnt vmcnt(0)
	v_pk_mul_f32 v[10:11], v[54:55], v[10:11]
	v_pk_mul_f32 v[14:15], v[42:43], v[14:15]
	v_pk_mul_f32 v[42:43], v[46:47], v[10:11]
	v_pk_mul_f32 v[10:11], v[38:39], v[10:11]
	v_pk_fma_f32 v[42:43], v[38:39], v[14:15], v[42:43]
	v_pk_fma_f32 v[10:11], v[46:47], v[14:15], v[10:11] neg_lo:[0,0,1] neg_hi:[0,0,1]
	v_and_b32_e32 v15, 0xffff0000, v12
	v_lshlrev_b32_e32 v14, 16, v12
	v_cvt_pk_bf16_f32 v148, v10, v11
	v_and_b32_e32 v11, 0xffff0000, v16
	v_lshlrev_b32_e32 v10, 16, v16
	v_pk_mul_f32 v[14:15], v[50:51], v[14:15] op_sel_hi:[0,1]
	v_pk_mul_f32 v[10:11], v[50:51], v[10:11] op_sel_hi:[0,1]
	v_pk_mul_f32 v[14:15], v[26:27], v[14:15]
	v_pk_mul_f32 v[10:11], v[30:31], v[10:11]
	v_pk_mul_f32 v[26:27], v[22:23], v[14:15]
	v_pk_mul_f32 v[14:15], v[18:19], v[14:15]
	v_pk_mul_f32 v[58:59], v[50:51], v[58:59] op_sel_hi:[0,1]
	v_pk_fma_f32 v[26:27], v[18:19], v[10:11], v[26:27]
	v_pk_fma_f32 v[10:11], v[22:23], v[10:11], v[14:15] neg_lo:[0,0,1] neg_hi:[0,0,1]
	v_and_b32_e32 v15, 0xffff0000, v13
	v_lshlrev_b32_e32 v14, 16, v13
	v_pk_mul_f32 v[56:57], v[56:57], v[58:59]
	v_cvt_pk_bf16_f32 v150, v10, v11
	v_and_b32_e32 v11, 0xffff0000, v17
	v_lshlrev_b32_e32 v10, 16, v17
	v_pk_mul_f32 v[12:13], v[50:51], v[14:15] op_sel_hi:[0,1]
	v_pk_mul_f32 v[58:59], v[48:49], v[56:57]
	v_pk_mul_f32 v[10:11], v[50:51], v[10:11] op_sel_hi:[0,1]
	v_pk_mul_f32 v[12:13], v[28:29], v[12:13]
	v_pk_fma_f32 v[58:59], v[40:41], v[44:45], v[58:59]
	v_pk_mul_f32 v[40:41], v[40:41], v[56:57]
	v_pk_mul_f32 v[10:11], v[32:33], v[10:11]
	v_pk_mul_f32 v[14:15], v[24:25], v[12:13]
	v_pk_mul_f32 v[12:13], v[20:21], v[12:13]
	v_pk_fma_f32 v[40:41], v[48:49], v[44:45], v[40:41] neg_lo:[0,0,1] neg_hi:[0,0,1]
	v_pk_fma_f32 v[14:15], v[20:21], v[10:11], v[14:15]
	v_pk_fma_f32 v[10:11], v[24:25], v[10:11], v[12:13] neg_lo:[0,0,1] neg_hi:[0,0,1]
	v_cvt_pk_bf16_f32 v149, v40, v41
	v_cvt_pk_bf16_f32 v144, v42, v43
	v_cvt_pk_bf16_f32 v145, v58, v59
	v_cvt_pk_bf16_f32 v146, v26, v27
	v_cvt_pk_bf16_f32 v147, v14, v15
	v_cvt_pk_bf16_f32 v151, v10, v11
	global_load_dwordx4 v[14:17], v[36:37], off offset:80
	global_load_dwordx4 v[22:25], v[36:37], off offset:64
	global_load_dwordx4 v[26:29], v0, s[8:9] offset:592
	global_load_dwordx4 v[30:33], v0, s[8:9] offset:576
	global_load_dwordx4 v[10:13], v[34:35], off offset:80
	s_nop 0
	global_load_dwordx4 v[34:37], v[34:35], off offset:64
	s_nop 0
	global_load_dwordx4 v[18:21], v0, s[8:9] offset:720
	global_load_dwordx4 v[38:41], v0, s[8:9] offset:704
	v_and_b32_e32 v43, 0xffff0000, v7
	v_lshlrev_b32_e32 v42, 16, v7
	v_pk_mul_f32 v[42:43], v[50:51], v[42:43] op_sel_hi:[0,1]
	v_and_b32_e32 v7, 0xffff0000, v6
	v_lshlrev_b32_e32 v6, 16, v6
	v_pk_mul_f32 v[6:7], v[50:51], v[6:7] op_sel_hi:[0,1]
	s_waitcnt vmcnt(4)
	v_pk_mul_f32 v[32:33], v[32:33], v[42:43]
	v_and_b32_e32 v43, 0xffff0000, v3
	v_lshlrev_b32_e32 v42, 16, v3
	v_and_b32_e32 v3, 0xffff0000, v2
	v_lshlrev_b32_e32 v2, 16, v2
	v_pk_mul_f32 v[2:3], v[50:51], v[2:3] op_sel_hi:[0,1]
	s_waitcnt vmcnt(0)
; DI unsigned pack_bf16(float lo, float hi) { f32x2 v = {lo, hi}; bf16v2 b = __builtin_convertvector(v, bf16v2); return __builtin_bit_cast(unsigned, b); }
; DI void attn_phase(const bf16_t* __restrict__ qraw, const bf16_t* __restrict__ kbuf, const bf16_t* __restrict__ vtb, bf16_t* __restrict__ obuf,
;                    const float* __restrict__ gq, const float* __restrict__ cosT, const float* __restrict__ sinT, bf16_t* sm, int x, int j) {
;     ...
;             if (hf == 0) { o1.x = pack_bf16(y1[0], y1[1]); o1.y = pack_bf16(y1[2], y1[3]); o2.x = pack_bf16(y2[0], y2[1]); o2.y = pack_bf16(y2[2], y2[3]); }
;             else { o1.z = pack_bf16(y1[0], y1[1]); o1.w = pack_bf16(y1[2], y1[3]); o2.z = pack_bf16(y2[0], y2[1]); o2.w = pack_bf16(y2[2], y2[3]); }
;           }
;           asm volatile("" : "+v"(o1), "+v"(o2));
;           qf[st] = __builtin_bit_cast(bf16x8, o1); qf[st + 2] = __builtin_bit_cast(bf16x8, o2);
;           __builtin_amdgcn_sched_barrier(0);
;         }
;       }
;       f32x16 oacc[4];
; #pragma unroll
;       for (int mt = 0; mt < 4; ++mt)
; #pragma unroll
;         for (int i = 0; i < 16; ++i) oacc[mt][i] = 0.f;
;       float m_run = -1e30f, l_run = 0.f;
;       const int nkt = 4 * qb + 4;
;       const bf16_t* kg = kbuf + (size_t)bh * S * QKH;
;       const bf16_t* vg = vtb + (size_t)bh * VH * SV;
;       u32x4 rk[3], rv[2];
;       const unsigned kg_off0 = (unsigned)(tid >> 3) * QKH + (unsigned)(tid & 7) * 8u;
;       const unsigned vg_off0 = (unsigned)(tid >> 3) * (unsigned)SV + (unsigned)(tid & 7) * 8u;
;       const unsigned kl_off = (unsigned)(tid >> 3) * KLS + (unsigned)(tid & 7) * 8u;
;       const unsigned vl_off = (unsigned)(tid >> 3) * VLS + (unsigned)(tid & 7) * 8u;
;     ...
;       ALOAD(0);
;     ...
;       ASTORE(0);
;       __syncthreads();
	v_pk_mul_f32 v[2:3], v[38:39], v[2:3]
	v_pk_mul_f32 v[6:7], v[30:31], v[6:7]
	v_pk_mul_f32 v[30:31], v[34:35], v[2:3]
	v_pk_mul_f32 v[2:3], v[22:23], v[2:3]
	v_pk_fma_f32 v[30:31], v[22:23], v[6:7], v[30:31]
	v_pk_fma_f32 v[2:3], v[34:35], v[6:7], v[2:3] neg_lo:[0,0,1] neg_hi:[0,0,1]
	v_and_b32_e32 v7, 0xffff0000, v4
	v_lshlrev_b32_e32 v6, 16, v4
	v_cvt_pk_bf16_f32 v156, v2, v3
	v_and_b32_e32 v3, 0xffff0000, v8
	v_lshlrev_b32_e32 v2, 16, v8
	v_pk_mul_f32 v[6:7], v[50:51], v[6:7] op_sel_hi:[0,1]
	v_pk_mul_f32 v[2:3], v[50:51], v[2:3] op_sel_hi:[0,1]
	v_pk_mul_f32 v[6:7], v[18:19], v[6:7]
	v_pk_mul_f32 v[2:3], v[26:27], v[2:3]
	v_pk_mul_f32 v[18:19], v[10:11], v[6:7]
	v_pk_mul_f32 v[6:7], v[14:15], v[6:7]
	v_pk_mul_f32 v[42:43], v[50:51], v[42:43] op_sel_hi:[0,1]
	v_pk_fma_f32 v[18:19], v[14:15], v[2:3], v[18:19]
	v_pk_fma_f32 v[2:3], v[10:11], v[2:3], v[6:7] neg_lo:[0,0,1] neg_hi:[0,0,1]
	v_and_b32_e32 v7, 0xffff0000, v5
	v_lshlrev_b32_e32 v6, 16, v5
	v_pk_mul_f32 v[40:41], v[40:41], v[42:43]
	v_cvt_pk_bf16_f32 v158, v2, v3
	v_and_b32_e32 v3, 0xffff0000, v9
	v_lshlrev_b32_e32 v2, 16, v9
	v_pk_mul_f32 v[4:5], v[50:51], v[6:7] op_sel_hi:[0,1]
	v_pk_mul_f32 v[42:43], v[36:37], v[40:41]
	v_pk_mul_f32 v[2:3], v[50:51], v[2:3] op_sel_hi:[0,1]
	v_pk_mul_f32 v[4:5], v[20:21], v[4:5]
	v_pk_fma_f32 v[42:43], v[24:25], v[32:33], v[42:43]
	v_pk_mul_f32 v[24:25], v[24:25], v[40:41]
	v_pk_mul_f32 v[2:3], v[28:29], v[2:3]
	v_pk_mul_f32 v[6:7], v[12:13], v[4:5]
	v_pk_mul_f32 v[4:5], v[16:17], v[4:5]
	v_pk_fma_f32 v[24:25], v[36:37], v[32:33], v[24:25] neg_lo:[0,0,1] neg_hi:[0,0,1]
	v_pk_fma_f32 v[6:7], v[16:17], v[2:3], v[6:7]
	v_pk_fma_f32 v[2:3], v[12:13], v[2:3], v[4:5] neg_lo:[0,0,1] neg_hi:[0,0,1]
	v_cvt_pk_bf16_f32 v157, v24, v25
	v_cvt_pk_bf16_f32 v152, v30, v31
	v_cvt_pk_bf16_f32 v153, v42, v43
	v_cvt_pk_bf16_f32 v154, v18, v19
	v_cvt_pk_bf16_f32 v155, v6, v7
	v_cvt_pk_bf16_f32 v159, v2, v3
	v_ashrrev_i32_e32 v8, 3, v53
	s_movk_i32 s1, 0xc0
	v_lshlrev_b32_e32 v2, 3, v53
	v_mul_lo_u32 v0, v8, s1
	v_and_b32_e32 v2, 56, v2
	s_movk_i32 s1, 0x4040
	v_or_b32_e32 v192, v0, v2
	v_mul_lo_u32 v0, v8, s1
	v_or_b32_e32 v193, v0, v2
	v_mov_b32_e32 v0, v192
	v_mov_b32_e32 v4, v193
	s_movk_i32 s1, 0xc8
	v_mov_b32_e32 v5, v1
	v_mad_u64_u32 v[188:189], s[2:3], v8, s1, v[2:3]
	v_lshl_add_u64 v[6:7], v[0:1], 1, s[38:39]
	v_lshl_add_u64 v[2:3], v[4:5], 1, s[70:71]
	global_load_dwordx4 v[160:163], v[6:7], off
	global_load_dwordx4 v[172:175], v[2:3], off
	v_add_u32_e32 v6, 64, v0
	v_mov_b32_e32 v7, v1
	v_lshl_add_u64 v[6:7], v[6:7], 1, s[38:39]
	v_add_u32_e32 v0, 0x80, v0
	global_load_dwordx4 v[164:167], v[6:7], off
	v_lshl_add_u64 v[6:7], v[0:1], 1, s[38:39]
	global_load_dwordx4 v[168:171], v[6:7], off
	v_add_u32_e32 v0, 0x101000, v4
	v_lshl_add_u64 v[2:3], v[0:1], 1, s[70:71]
	global_load_dwordx4 v[176:179], v[2:3], off
	v_lshl_add_u32 v0, v188, 1, 0
	v_mov_b32_e32 v14, v1
	v_mov_b32_e32 v15, v1
	v_mul_u32_u24_e32 v195, 0x190, v51
	v_mul_u32_u24_e32 v191, 0x90, v51
	v_or_b32_e32 v190, v186, v51
	v_lshlrev_b32_e32 v189, 2, v52
	v_mov_b32_e32 v2, v1
	v_mov_b32_e32 v3, v1
	v_mov_b32_e32 v4, v1
	v_mov_b32_e32 v6, v1
	v_mov_b32_e32 v7, v1
	v_mov_b32_e32 v9, v1
	v_mov_b32_e32 v10, v1
	v_mov_b32_e32 v11, v1
	v_mov_b32_e32 v12, v1
	v_mov_b32_e32 v13, v1
	v_or_b32_e32 v196, 31, v186
	s_or_b32 s90, s0, 0xc0
	v_mov_b32_e32 v198, 0
	v_mov_b32_e32 v199, 0xf149f2ca
	v_mov_b32_e32 v197, 0
	s_mov_b64 s[54:55], s[58:59]
	s_mov_b64 s[84:85], s[14:15]
	s_waitcnt vmcnt(4)
	ds_write_b128 v0, v[160:163]
	s_waitcnt vmcnt(2)
	ds_write_b128 v0, v[164:167] offset:128
	s_waitcnt vmcnt(1)
	ds_write_b128 v0, v[168:171] offset:256
	v_lshlrev_b32_e32 v0, 7, v8
	v_sub_u32_e32 v194, v188, v0
	s_mov_b32 s98, 0
	v_lshl_add_u32 v0, v194, 1, 0
	ds_write_b128 v0, v[172:175] offset:25600
	s_waitcnt vmcnt(0)
	ds_write_b128 v0, v[176:179] offset:34816
	v_mov_b32_e32 v0, v1
	v_mov_b32_e32 v8, v1
	v_mov_b64_e32 v[30:31], v[14:15]
	v_mov_b64_e32 v[46:47], v[14:15]
	v_mov_b64_e32 v[62:63], v[14:15]
	v_mov_b64_e32 v[78:79], v[14:15]
	v_mov_b64_e32 v[28:29], v[12:13]
	v_mov_b64_e32 v[26:27], v[10:11]
	v_mov_b64_e32 v[24:25], v[8:9]
	v_mov_b64_e32 v[22:23], v[6:7]
	v_mov_b64_e32 v[20:21], v[4:5]
	v_mov_b64_e32 v[18:19], v[2:3]
	v_mov_b64_e32 v[16:17], v[0:1]
	v_mov_b64_e32 v[44:45], v[12:13]
	v_mov_b64_e32 v[42:43], v[10:11]
	v_mov_b64_e32 v[40:41], v[8:9]
	v_mov_b64_e32 v[38:39], v[6:7]
	v_mov_b64_e32 v[36:37], v[4:5]
	v_mov_b64_e32 v[34:35], v[2:3]
	v_mov_b64_e32 v[32:33], v[0:1]
	v_mov_b64_e32 v[60:61], v[12:13]
	v_mov_b64_e32 v[58:59], v[10:11]
	v_mov_b64_e32 v[56:57], v[8:9]
	v_mov_b64_e32 v[54:55], v[6:7]
	v_mov_b64_e32 v[52:53], v[4:5]
	v_mov_b64_e32 v[50:51], v[2:3]
	v_mov_b64_e32 v[48:49], v[0:1]
	v_mov_b64_e32 v[76:77], v[12:13]
	v_mov_b64_e32 v[74:75], v[10:11]
	v_mov_b64_e32 v[72:73], v[8:9]
	v_mov_b64_e32 v[70:71], v[6:7]
	v_mov_b64_e32 v[68:69], v[4:5]
	v_mov_b64_e32 v[66:67], v[2:3]
	v_mov_b64_e32 v[64:65], v[0:1]
	s_waitcnt lgkmcnt(0)
	s_barrier
	v_cmp_le_i32_e32 vcc, s31, v196
	v_cmp_gt_i32_e64 s[0:1], s31, v196
	s_and_saveexec_b64 s[2:3], s[0:1]
	s_cbranch_execz .LBB0_1282

; #define MFMA(a, b, c) __builtin_amdgcn_mfma_f32_32x32x16_bf16((a), (b), (c), 0, 0, 0)
; DI void attn_phase(const bf16_t* __restrict__ qraw, const bf16_t* __restrict__ kbuf, const bf16_t* __restrict__ vtb, bf16_t* __restrict__ obuf,
;                    const float* __restrict__ gq, const float* __restrict__ cosT, const float* __restrict__ sinT, bf16_t* sm, int x, int j) {
;     ...
;       for (int kt = 0; kt < nkt; ++kt) {
;         const bf16_t* smk = sm + (kt & 1) * ATT_STG_EL;
;         const bf16_t* smv = smk + K_EL;
;         const bool act_tile = (kt * 64 <= q0 + 31);
;         if (!act_tile && kt + 1 < nkt) ALOAD(kt + 1);
;         __builtin_amdgcn_sched_barrier(0);
;         if (act_tile) {
;         f32x16 sacc[2];
; #pragma unroll
;         for (int mt = 0; mt < 2; ++mt)
; #pragma unroll
;           for (int i = 0; i < 16; ++i) sacc[mt][i] = 0.f;
;         const bf16_t* kp = smk + r * KLS + h * 8;
;         {
;           bf16x8 ka = *(const bf16x8*)(kp), kb = *(const bf16x8*)(kp + 32 * KLS);
;           __builtin_amdgcn_sched_barrier(0);
;           if (kt + 1 < nkt) ALOAD(kt + 1);
;           __builtin_amdgcn_sched_barrier(0);
; #pragma unroll
;           for (int st = 0; st < 12; ++st) {
;             bf16x8 na = ka, nbq = kb;
;             if (st + 1 < 12) { na = *(const bf16x8*)(kp + (st + 1) * 16); nbq = *(const bf16x8*)(kp + 32 * KLS + (st + 1) * 16); }
;             sacc[0] = MFMA(ka, qf[st], sacc[0]);
;             sacc[1] = MFMA(kb, qf[st], sacc[1]);
;             ka = na; kb = nbq;
;             __builtin_amdgcn_sched_barrier(0);
;           }
;         }
;         bf16x8 va[2][4];
;         {
;           const bf16_t* vp0 = smv + r * VLS + h * 8;
; #pragma unroll
;           for (int mt = 0; mt < 4; ++mt) va[0][mt] = *(const bf16x8*)(vp0 + mt * 32 * VLS);
;         }
.LBB0_1282:
	s_or_b64 exec, exec, s[2:3]
	s_and_saveexec_b64 s[0:1], vcc
	s_xor_b64 s[0:1], exec, s[0:1]
	s_cbranch_execz .LBB0_1288
	s_bitcmp1_b32 s92, 0
	s_cselect_b32 s2, 0, 0xac00
	s_add_i32 vcc_lo, s2, 0
	v_lshlrev_b32_e32 v180, 1, v187
	v_add3_u32 v181, vcc_lo, v195, v180
	ds_read_b128 v[2:5], v181
	ds_read_b128 v[6:9], v181 offset:12800
	v_mov_b32_e32 v0, v192
	v_mov_b32_e32 v10, v193
	s_add_u32 s2, s34, s54
	s_addc_u32 s3, s35, s55
	v_lshl_add_u64 v[12:13], v[0:1], 1, s[2:3]
	v_add_u32_e32 v14, 64, v0
	v_mov_b32_e32 v15, v1
	v_add_u32_e32 v0, 0x80, v0
	v_lshl_add_u64 v[14:15], v[14:15], 1, s[2:3]
	global_load_dwordx4 v[160:163], v[12:13], off
	global_load_dwordx4 v[164:167], v[14:15], off
	v_lshl_add_u64 v[12:13], v[0:1], 1, s[2:3]
	s_add_u32 s2, s34, s84
	v_mov_b32_e32 v11, v1
	s_addc_u32 s3, s35, s85
	v_add_u32_e32 v0, 0x101000, v10
	v_lshl_add_u64 v[14:15], v[10:11], 1, s[2:3]
	v_lshl_add_u64 v[10:11], v[0:1], 1, s[2:3]
	global_load_dwordx4 v[168:171], v[12:13], off
	global_load_dwordx4 v[172:175], v[14:15], off
	global_load_dwordx4 v[176:179], v[10:11], off
	s_waitcnt lgkmcnt(1)
	v_mfma_f32_32x32x16_bf16 v[96:111], v[2:5], v[112:115], 0
	ds_read_b128 v[2:5], v181 offset:32
	ds_read_b128 v[10:13], v181 offset:12832
	s_waitcnt lgkmcnt(2)
	v_mfma_f32_32x32x16_bf16 v[80:95], v[6:9], v[112:115], 0
	s_waitcnt lgkmcnt(1)
	v_mfma_f32_32x32x16_bf16 v[96:111], v[2:5], v[116:119], v[96:111]
	ds_read_b128 v[2:5], v181 offset:64
	ds_read_b128 v[6:9], v181 offset:12864
	s_waitcnt lgkmcnt(2)
	v_mfma_f32_32x32x16_bf16 v[80:95], v[10:13], v[116:119], v[80:95]
	s_waitcnt lgkmcnt(1)
	v_mfma_f32_32x32x16_bf16 v[96:111], v[2:5], v[120:123], v[96:111]
	ds_read_b128 v[2:5], v181 offset:96
	ds_read_b128 v[10:13], v181 offset:12896
	s_waitcnt lgkmcnt(2)
	v_mfma_f32_32x32x16_bf16 v[80:95], v[6:9], v[120:123], v[80:95]
	s_waitcnt lgkmcnt(1)
	v_mfma_f32_32x32x16_bf16 v[96:111], v[2:5], v[124:127], v[96:111]
	ds_read_b128 v[2:5], v181 offset:128
	ds_read_b128 v[6:9], v181 offset:12928
	s_waitcnt lgkmcnt(2)
	v_mfma_f32_32x32x16_bf16 v[80:95], v[10:13], v[124:127], v[80:95]
	s_waitcnt lgkmcnt(1)
	v_mfma_f32_32x32x16_bf16 v[96:111], v[2:5], v[128:131], v[96:111]
	ds_read_b128 v[2:5], v181 offset:160
	ds_read_b128 v[10:13], v181 offset:12960
	s_waitcnt lgkmcnt(2)
	v_mfma_f32_32x32x16_bf16 v[80:95], v[6:9], v[128:131], v[80:95]
	s_waitcnt lgkmcnt(1)
	v_mfma_f32_32x32x16_bf16 v[96:111], v[2:5], v[132:135], v[96:111]
	ds_read_b128 v[2:5], v181 offset:192
	ds_read_b128 v[6:9], v181 offset:12992
	s_waitcnt lgkmcnt(2)
	v_mfma_f32_32x32x16_bf16 v[80:95], v[10:13], v[132:135], v[80:95]
	s_waitcnt lgkmcnt(1)
	v_mfma_f32_32x32x16_bf16 v[96:111], v[2:5], v[136:139], v[96:111]
	ds_read_b128 v[2:5], v181 offset:224
	ds_read_b128 v[10:13], v181 offset:13024
	s_waitcnt lgkmcnt(2)
	v_mfma_f32_32x32x16_bf16 v[80:95], v[6:9], v[136:139], v[80:95]
	s_waitcnt lgkmcnt(1)
	v_mfma_f32_32x32x16_bf16 v[96:111], v[2:5], v[140:143], v[96:111]
	ds_read_b128 v[2:5], v181 offset:256
	ds_read_b128 v[6:9], v181 offset:13056
	s_waitcnt lgkmcnt(2)
	v_mfma_f32_32x32x16_bf16 v[80:95], v[10:13], v[140:143], v[80:95]
	s_waitcnt lgkmcnt(1)
	v_mfma_f32_32x32x16_bf16 v[96:111], v[2:5], v[148:151], v[96:111]
	ds_read_b128 v[2:5], v181 offset:288
	ds_read_b128 v[10:13], v181 offset:13088
	s_waitcnt lgkmcnt(2)
	v_mfma_f32_32x32x16_bf16 v[80:95], v[6:9], v[148:151], v[80:95]
	s_waitcnt lgkmcnt(1)
	v_mfma_f32_32x32x16_bf16 v[96:111], v[2:5], v[156:159], v[96:111]
	ds_read_b128 v[2:5], v181 offset:320
	ds_read_b128 v[6:9], v181 offset:13120
	s_waitcnt lgkmcnt(2)
	v_mfma_f32_32x32x16_bf16 v[80:95], v[10:13], v[156:159], v[80:95]
	s_waitcnt lgkmcnt(1)
	v_mfma_f32_32x32x16_bf16 v[96:111], v[2:5], v[144:147], v[96:111]
	ds_read_b128 v[202:205], v181 offset:352
	ds_read_b128 v[2:5], v181 offset:13152
	s_waitcnt lgkmcnt(2)
	v_mfma_f32_32x32x16_bf16 v[80:95], v[6:9], v[144:147], v[80:95]
	s_waitcnt lgkmcnt(0)
	v_mfma_f32_32x32x16_bf16 v[80:95], v[2:5], v[152:155], v[80:95]
	v_add3_u32 v200, s98, v191, v180
	v_mfma_f32_32x32x16_bf16 v[96:111], v[202:205], v[152:155], v[96:111]
	ds_read_b128 v[180:183], v200 offset:25600
	ds_read_b128 v[10:13], v200 offset:30208
	ds_read_b128 v[6:9], v200 offset:34816
	ds_read_b128 v[2:5], v200 offset:39424
	s_add_i32 s2, s31, 63
	v_cmp_gt_i32_e32 vcc, s2, v186
	s_and_saveexec_b64 s[2:3], vcc
	s_cbranch_execz .LBB0_1285
; DI int crow(int i, int h) { return (i & 3) + 8 * (i >> 2) + 4 * h; }
; DI void attn_phase(const bf16_t* __restrict__ qraw, const bf16_t* __restrict__ kbuf, const bf16_t* __restrict__ vtb, bf16_t* __restrict__ obuf,
;                    const float* __restrict__ gq, const float* __restrict__ cosT, const float* __restrict__ sinT, bf16_t* sm, int x, int j) {
;     ...
;         if (kt * 64 + 63 > q0) {
;           const int qpos = q0 + r;
; #pragma unroll
;           for (int mt = 0; mt < 2; ++mt)
; #pragma unroll
;             for (int i = 0; i < 16; ++i) { const int key = kt * 64 + mt * 32 + crow(i, h); if (key > qpos) sacc[mt][i] = -INFINITY; }
;         }
	v_add_u32_e32 v0, s31, v189
	v_cmp_gt_i32_e32 vcc, v0, v190
	s_nop 1
	v_cndmask_b32_e32 v14, v96, v220, vcc
	v_cmp_lt_i32_e32 vcc, v0, v190
	s_nop 1
	v_cndmask_b32_e32 v96, v14, v96, vcc
	v_add_u32_e32 v14, 2, v0
	v_cndmask_b32_e32 v97, v220, v97, vcc
	v_cmp_le_i32_e32 vcc, v14, v190
	v_add_u32_e32 v14, 3, v0
	s_nop 0
	v_cndmask_b32_e32 v98, v220, v98, vcc
	v_cmp_le_i32_e32 vcc, v14, v190
	v_add_u32_e32 v14, 8, v0
	s_nop 0
	v_cndmask_b32_e32 v99, v220, v99, vcc
	v_cmp_le_i32_e32 vcc, v14, v190
	v_add_u32_e32 v14, 9, v0
	s_nop 0
	v_cndmask_b32_e32 v100, v220, v100, vcc
	v_cmp_le_i32_e32 vcc, v14, v190
	v_add_u32_e32 v14, 10, v0
	s_nop 0
	v_cndmask_b32_e32 v101, v220, v101, vcc
	v_cmp_le_i32_e32 vcc, v14, v190
	v_add_u32_e32 v14, 11, v0
	s_nop 0
	v_cndmask_b32_e32 v102, v220, v102, vcc
	v_cmp_le_i32_e32 vcc, v14, v190
	v_add_u32_e32 v14, 16, v0
	s_nop 0
	v_cndmask_b32_e32 v103, v220, v103, vcc
	v_cmp_le_i32_e32 vcc, v14, v190
	v_add_u32_e32 v14, 17, v0
	s_nop 0
	v_cndmask_b32_e32 v104, v220, v104, vcc
	v_cmp_le_i32_e32 vcc, v14, v190
	v_add_u32_e32 v14, 18, v0
	s_nop 0
	v_cndmask_b32_e32 v105, v220, v105, vcc
	v_cmp_le_i32_e32 vcc, v14, v190
	v_add_u32_e32 v14, 19, v0
	s_nop 0
	v_cndmask_b32_e32 v106, v220, v106, vcc
	v_cmp_le_i32_e32 vcc, v14, v190
	v_add_u32_e32 v14, 24, v0
	s_nop 0
	v_cndmask_b32_e32 v107, v220, v107, vcc
	v_cmp_le_i32_e32 vcc, v14, v190
	v_add_u32_e32 v14, 25, v0
	s_nop 0
	v_cndmask_b32_e32 v108, v220, v108, vcc
	v_cmp_le_i32_e32 vcc, v14, v190
	v_add_u32_e32 v14, 26, v0
	s_nop 0
	v_cndmask_b32_e32 v109, v220, v109, vcc
	v_cmp_le_i32_e32 vcc, v14, v190
	v_add_u32_e32 v14, 27, v0
	s_nop 0
	v_cndmask_b32_e32 v110, v220, v110, vcc
	v_cmp_le_i32_e32 vcc, v14, v190
	v_add_u32_e32 v14, 32, v0
	s_nop 0
	v_cndmask_b32_e32 v111, v220, v111, vcc
	v_cmp_le_i32_e32 vcc, v14, v190
	v_add_u32_e32 v14, 33, v0
	s_nop 0
	v_cndmask_b32_e32 v80, v220, v80, vcc
	v_cmp_le_i32_e32 vcc, v14, v190
	v_add_u32_e32 v14, 34, v0
	s_nop 0
	v_cndmask_b32_e32 v81, v220, v81, vcc
	v_cmp_le_i32_e32 vcc, v14, v190
	v_add_u32_e32 v14, 35, v0
	s_nop 0
	v_cndmask_b32_e32 v82, v220, v82, vcc
	v_cmp_le_i32_e32 vcc, v14, v190
	v_add_u32_e32 v14, 40, v0
	s_nop 0
	v_cndmask_b32_e32 v83, v220, v83, vcc
	v_cmp_le_i32_e32 vcc, v14, v190
	v_add_u32_e32 v14, 41, v0
	s_nop 0
	v_cndmask_b32_e32 v84, v220, v84, vcc
	v_cmp_le_i32_e32 vcc, v14, v190
	v_add_u32_e32 v14, 42, v0
	s_nop 0
	v_cndmask_b32_e32 v85, v220, v85, vcc
	v_cmp_le_i32_e32 vcc, v14, v190
	v_add_u32_e32 v14, 43, v0
	s_nop 0
	v_cndmask_b32_e32 v86, v220, v86, vcc
	v_cmp_le_i32_e32 vcc, v14, v190
	v_add_u32_e32 v14, 48, v0
	s_nop 0
	v_cndmask_b32_e32 v87, v220, v87, vcc
	v_cmp_le_i32_e32 vcc, v14, v190
	v_add_u32_e32 v14, 49, v0
	s_nop 0
	v_cndmask_b32_e32 v88, v220, v88, vcc
	v_cmp_le_i32_e32 vcc, v14, v190
	v_add_u32_e32 v14, 50, v0
	s_nop 0
	v_cndmask_b32_e32 v89, v220, v89, vcc
	v_cmp_le_i32_e32 vcc, v14, v190
	v_add_u32_e32 v14, 51, v0
	s_nop 0
	v_cndmask_b32_e32 v90, v220, v90, vcc
	v_cmp_le_i32_e32 vcc, v14, v190
	v_add_u32_e32 v14, 56, v0
	s_nop 0
	v_cndmask_b32_e32 v91, v220, v91, vcc
	v_cmp_le_i32_e32 vcc, v14, v190
	v_add_u32_e32 v14, 57, v0
	s_nop 0
	v_cndmask_b32_e32 v92, v220, v92, vcc
	v_cmp_le_i32_e32 vcc, v14, v190
	v_add_u32_e32 v14, 58, v0
	v_add_u32_e32 v0, 59, v0
	v_cndmask_b32_e32 v93, v220, v93, vcc
	v_cmp_le_i32_e32 vcc, v14, v190
	s_nop 1
	v_cndmask_b32_e32 v94, v220, v94, vcc
	v_cmp_le_i32_e32 vcc, v0, v190
	s_nop 1
	v_cndmask_b32_e32 v95, v220, v95, vcc

; #define MFMA(a, b, c) __builtin_amdgcn_mfma_f32_32x32x16_bf16((a), (b), (c), 0, 0, 0)
; DI void attn_phase(const bf16_t* __restrict__ qraw, const bf16_t* __restrict__ kbuf, const bf16_t* __restrict__ vtb, bf16_t* __restrict__ obuf,
;                    const float* __restrict__ gq, const float* __restrict__ cosT, const float* __restrict__ sinT, bf16_t* sm, int x, int j) {
;     ...
;         const bf16_t* kp = smk + r * KLS + h * 8;
;         {
;           bf16x8 ka = *(const bf16x8*)(kp), kb = *(const bf16x8*)(kp + 32 * KLS);
;           __builtin_amdgcn_sched_barrier(0);
;           if (kt + 1 < nkt) ALOAD(kt + 1);
;           __builtin_amdgcn_sched_barrier(0);
; #pragma unroll
;           for (int st = 0; st < 12; ++st) {
;             bf16x8 na = ka, nbq = kb;
;             if (st + 1 < 12) { na = *(const bf16x8*)(kp + (st + 1) * 16); nbq = *(const bf16x8*)(kp + 32 * KLS + (st + 1) * 16); }
;             sacc[0] = MFMA(ka, qf[st], sacc[0]);
;             sacc[1] = MFMA(kb, qf[st], sacc[1]);
;             ka = na; kb = nbq;
;             __builtin_amdgcn_sched_barrier(0);
;           }
;     ...
;         if (kt + 1 < nkt) ASTORE((kt + 1) & 1);
;         __syncthreads();
.LBB0_1288:
	s_andn2_saveexec_b64 s[0:1], s[0:1]
	v_add_u32_e32 v197, 1, v197
	v_mov_b32_e32 v14, v198
	v_mov_b32_e32 v15, v199
	s_or_b64 exec, exec, s[0:1]
	s_bitcmp1_b32 s92, 0
	s_cselect_b32 s0, 0xac00, 0
	s_cmp_eq_u32 s98, 0
	s_mov_b32 s99, 0xf400
	s_cselect_b32 s99, 0xac00, s99
	s_cmp_eq_u32 s98, 0xf400
	s_cselect_b32 s99, 0, s99
	s_add_i32 s2, s0, 0
	s_add_u32 s84, s84, 0x80
	s_addc_u32 s85, s85, 0
	s_add_u32 s54, s54, 0x6000
	v_lshl_add_u32 v0, v188, 1, s2
	s_addc_u32 s55, s55, 0
	s_add_i32 s31, s31, 64
	s_add_i32 s92, s92, 1
	s_waitcnt vmcnt(4)
	ds_write_b128 v0, v[160:163]
	s_waitcnt vmcnt(3)
	ds_write_b128 v0, v[164:167] offset:128
	s_waitcnt vmcnt(2)
	ds_write_b128 v0, v[168:171] offset:256
	v_lshl_add_u32 v0, v194, 1, s99
	s_cmp_eq_u32 s90, s31
	s_waitcnt vmcnt(1)
	ds_write_b128 v0, v[172:175] offset:25600
	s_waitcnt vmcnt(0)
	ds_write_b128 v0, v[176:179] offset:34816
	s_mov_b32 s98, s99
	s_waitcnt lgkmcnt(0)
	s_barrier
	s_cbranch_scc1 .LBB0_1292
	v_mov_b32_e32 v199, v15
	v_mov_b32_e32 v198, v14
	v_readfirstlane_b32 s99, v211
	s_cmp_lt_u32 s99, 0x100
	s_cbranch_scc1 .Lrot_resume
	s_sub_i32 s99, s90, 0x100
	s_cmp_gt_i32 s31, s99
	s_cbranch_scc1 .Lrot_resume
	s_branch .Lrot_entry
.Lrot_resume:
	v_cmp_le_i32_e32 vcc, s31, v196
	v_cmp_gt_i32_e64 s[0:1], s31, v196
	s_and_saveexec_b64 s[2:3], s[0:1]
	s_cbranch_execnz .LBB0_1281
	s_branch .LBB0_1282
.Lrot_entry:
	s_bitcmp1_b32 s92, 0
	s_cselect_b32 s2, 0, 0xac00
	s_add_i32 vcc_lo, s2, 0
	v_lshlrev_b32_e32 v180, 1, v187
	v_add3_u32 v181, vcc_lo, v195, v180
	ds_read_b128 v[2:5], v181
	ds_read_b128 v[6:9], v181 offset:12800
	v_mov_b32_e32 v0, v192
	v_mov_b32_e32 v10, v193
	s_add_u32 s2, s34, s54
	s_addc_u32 s3, s35, s55
	v_lshl_add_u64 v[12:13], v[0:1], 1, s[2:3]
	v_add_u32_e32 v14, 64, v0
	v_mov_b32_e32 v15, v1
	v_add_u32_e32 v0, 0x80, v0
	v_lshl_add_u64 v[14:15], v[14:15], 1, s[2:3]
	global_load_dwordx4 v[160:163], v[12:13], off
	global_load_dwordx4 v[164:167], v[14:15], off
	v_lshl_add_u64 v[12:13], v[0:1], 1, s[2:3]
	s_add_u32 s2, s34, s84
	v_mov_b32_e32 v11, v1
	s_addc_u32 s3, s35, s85
	v_add_u32_e32 v0, 0x101000, v10
	v_lshl_add_u64 v[14:15], v[10:11], 1, s[2:3]
	v_lshl_add_u64 v[10:11], v[0:1], 1, s[2:3]
	global_load_dwordx4 v[168:171], v[12:13], off
	global_load_dwordx4 v[172:175], v[14:15], off
	global_load_dwordx4 v[176:179], v[10:11], off
	s_waitcnt lgkmcnt(1)
	v_mfma_f32_32x32x16_bf16 v[96:111], v[2:5], v[112:115], 0
	ds_read_b128 v[2:5], v181 offset:32
	ds_read_b128 v[10:13], v181 offset:12832
	s_waitcnt lgkmcnt(2)
	v_mfma_f32_32x32x16_bf16 v[80:95], v[6:9], v[112:115], 0
	s_waitcnt lgkmcnt(1)
	v_mfma_f32_32x32x16_bf16 v[96:111], v[2:5], v[116:119], v[96:111]
	ds_read_b128 v[2:5], v181 offset:64
	ds_read_b128 v[6:9], v181 offset:12864
	s_waitcnt lgkmcnt(2)
	v_mfma_f32_32x32x16_bf16 v[80:95], v[10:13], v[116:119], v[80:95]
	s_waitcnt lgkmcnt(1)
	v_mfma_f32_32x32x16_bf16 v[96:111], v[2:5], v[120:123], v[96:111]
	ds_read_b128 v[2:5], v181 offset:96
	ds_read_b128 v[10:13], v181 offset:12896
	s_waitcnt lgkmcnt(2)
	v_mfma_f32_32x32x16_bf16 v[80:95], v[6:9], v[120:123], v[80:95]
	s_waitcnt lgkmcnt(1)
	v_mfma_f32_32x32x16_bf16 v[96:111], v[2:5], v[124:127], v[96:111]
	ds_read_b128 v[2:5], v181 offset:128
	ds_read_b128 v[6:9], v181 offset:12928
	s_waitcnt lgkmcnt(2)
	v_mfma_f32_32x32x16_bf16 v[80:95], v[10:13], v[124:127], v[80:95]
	s_waitcnt lgkmcnt(1)
	v_mfma_f32_32x32x16_bf16 v[96:111], v[2:5], v[128:131], v[96:111]
	ds_read_b128 v[2:5], v181 offset:160
	ds_read_b128 v[10:13], v181 offset:12960
	s_waitcnt lgkmcnt(2)
	v_mfma_f32_32x32x16_bf16 v[80:95], v[6:9], v[128:131], v[80:95]
	s_waitcnt lgkmcnt(1)
	v_mfma_f32_32x32x16_bf16 v[96:111], v[2:5], v[132:135], v[96:111]
	ds_read_b128 v[2:5], v181 offset:192
	ds_read_b128 v[6:9], v181 offset:12992
	s_waitcnt lgkmcnt(2)
	v_mfma_f32_32x32x16_bf16 v[80:95], v[10:13], v[132:135], v[80:95]
	s_waitcnt lgkmcnt(1)
	v_mfma_f32_32x32x16_bf16 v[96:111], v[2:5], v[136:139], v[96:111]
	ds_read_b128 v[2:5], v181 offset:224
	ds_read_b128 v[10:13], v181 offset:13024
	s_waitcnt lgkmcnt(2)
	v_mfma_f32_32x32x16_bf16 v[80:95], v[6:9], v[136:139], v[80:95]
	s_waitcnt lgkmcnt(1)
	v_mfma_f32_32x32x16_bf16 v[96:111], v[2:5], v[140:143], v[96:111]
	ds_read_b128 v[2:5], v181 offset:256
	ds_read_b128 v[6:9], v181 offset:13056
	s_waitcnt lgkmcnt(2)
	v_mfma_f32_32x32x16_bf16 v[80:95], v[10:13], v[140:143], v[80:95]
	s_waitcnt lgkmcnt(1)
	v_mfma_f32_32x32x16_bf16 v[96:111], v[2:5], v[148:151], v[96:111]
	ds_read_b128 v[2:5], v181 offset:288
	ds_read_b128 v[10:13], v181 offset:13088
	s_waitcnt lgkmcnt(2)
	v_mfma_f32_32x32x16_bf16 v[80:95], v[6:9], v[148:151], v[80:95]
	s_waitcnt lgkmcnt(1)
	v_mfma_f32_32x32x16_bf16 v[96:111], v[2:5], v[156:159], v[96:111]
	ds_read_b128 v[2:5], v181 offset:320
	ds_read_b128 v[6:9], v181 offset:13120
	s_waitcnt lgkmcnt(2)
	v_mfma_f32_32x32x16_bf16 v[80:95], v[10:13], v[156:159], v[80:95]
	s_waitcnt lgkmcnt(1)
	v_mfma_f32_32x32x16_bf16 v[96:111], v[2:5], v[144:147], v[96:111]
	ds_read_b128 v[202:205], v181 offset:352
	ds_read_b128 v[2:5], v181 offset:13152
	s_waitcnt lgkmcnt(2)
	v_mfma_f32_32x32x16_bf16 v[80:95], v[6:9], v[144:147], v[80:95]
	s_waitcnt lgkmcnt(0)
; DI int crow(int i, int h) { return (i & 3) + 8 * (i >> 2) + 4 * h; }
; DI float xmax32(float v) { const u32x2 r = __builtin_amdgcn_permlane32_swap(__float_as_uint(v), __float_as_uint(v), false, false); return fmaxf(__uint_as_float(r.x), __uint_as_float(r.y)); }
; DI float xsum32(float v) { const u32x2 r = __builtin_amdgcn_permlane32_swap(__float_as_uint(v), __float_as_uint(v), false, false); return __uint_as_float(r.x) + __uint_as_float(r.y); }
; #define MFMA(a, b, c) __builtin_amdgcn_mfma_f32_32x32x16_bf16((a), (b), (c), 0, 0, 0)
; DI void attn_phase(const bf16_t* __restrict__ qraw, const bf16_t* __restrict__ kbuf, const bf16_t* __restrict__ vtb, bf16_t* __restrict__ obuf,
;                    const float* __restrict__ gq, const float* __restrict__ cosT, const float* __restrict__ sinT, bf16_t* sm, int x, int j) {
;     ...
;             sacc[0] = MFMA(ka, qf[st], sacc[0]);
;             sacc[1] = MFMA(kb, qf[st], sacc[1]);
;             ka = na; kb = nbq;
;             __builtin_amdgcn_sched_barrier(0);
;           }
;         }
;         bf16x8 va[2][4];
;         {
;           const bf16_t* vp0 = smv + r * VLS + h * 8;
; #pragma unroll
;           for (int mt = 0; mt < 4; ++mt) va[0][mt] = *(const bf16x8*)(vp0 + mt * 32 * VLS);
;         }
;         if (kt * 64 + 63 > q0) {
;           const int qpos = q0 + r;
; #pragma unroll
;           for (int mt = 0; mt < 2; ++mt)
; #pragma unroll
;             for (int i = 0; i < 16; ++i) { const int key = kt * 64 + mt * 32 + crow(i, h); if (key > qpos) sacc[mt][i] = -INFINITY; }
;         }
;         float mx = sacc[0][0];
; #pragma unroll
;         for (int mt = 0; mt < 2; ++mt)
; #pragma unroll
;           for (int i = 0; i < 16; ++i) mx = fmaxf(mx, sacc[mt][i]);
;         mx = xmax32(mx);
;         const float m_new = fmaxf(m_run, mx);
;         const float alpha = __builtin_amdgcn_exp2f(m_run - m_new);
;         m_run = m_new;
;         float rs = 0.f;
; #pragma unroll
;         for (int mt = 0; mt < 2; ++mt)
; #pragma unroll
;           for (int i = 0; i < 16; ++i) { const float pv = __builtin_amdgcn_exp2f(sacc[mt][i] - m_new); sacc[mt][i] = pv; rs += pv; }
;         rs = xsum32(rs);
;         l_run = l_run * alpha + rs;
;         if (__any(alpha != 1.f)) {
; #pragma unroll
;           for (int mt = 0; mt < 4; ++mt)
; #pragma unroll
;             for (int i = 0; i < 16; ++i) oacc[mt][i] *= alpha;
;         }
	v_mfma_f32_32x32x16_bf16 v[80:95], v[2:5], v[152:155], v[80:95]
	v_mfma_f32_32x32x16_bf16 v[96:111], v[202:205], v[152:155], v[96:111]
	s_nop 7
	s_nop 4
	s_nop 2
	v_max_f32_e32 v0, v97, v97
	v_max_f32_e32 v14, v96, v96
	v_max_f32_e32 v0, v14, v0
	v_max3_f32 v0, v0, v98, v99
	v_max3_f32 v0, v0, v100, v101
	v_max3_f32 v0, v0, v102, v103
	v_max3_f32 v0, v0, v104, v105
	v_max3_f32 v0, v0, v106, v107
	v_max3_f32 v0, v0, v108, v109
	v_max3_f32 v0, v0, v110, v111
	v_max3_f32 v0, v0, v80, v81
	v_max3_f32 v0, v0, v82, v83
	v_max3_f32 v0, v0, v84, v85
	v_max3_f32 v0, v0, v86, v87
	v_max3_f32 v0, v0, v88, v89
	v_max3_f32 v0, v0, v90, v91
	v_max3_f32 v0, v0, v92, v93
	v_max3_f32 v0, v0, v94, v95
	v_mov_b32_e32 v14, v0
	s_nop 1
	v_permlane32_swap_b32_e32 v0, v14
	v_max3_f32 v15, v199, v0, v14
	v_sub_f32_e32 v14, v96, v15
	v_exp_f32_e32 v96, v14
	v_sub_f32_e32 v14, v97, v15
	v_exp_f32_e32 v97, v14
	v_sub_f32_e32 v14, v98, v15
	v_exp_f32_e32 v98, v14
	v_sub_f32_e32 v14, v99, v15
	v_exp_f32_e32 v99, v14
	v_sub_f32_e32 v100, v100, v15
	v_add_f32_e32 v14, 0, v96
	v_exp_f32_e32 v100, v100
	v_sub_f32_e32 v101, v101, v15
	v_add_f32_e32 v14, v97, v14
	v_exp_f32_e32 v101, v101
	v_sub_f32_e32 v102, v102, v15
	v_add_f32_e32 v14, v98, v14
	v_exp_f32_e32 v102, v102
	v_sub_f32_e32 v103, v103, v15
	v_add_f32_e32 v14, v99, v14
	v_exp_f32_e32 v103, v103
	v_sub_f32_e32 v104, v104, v15
	v_add_f32_e32 v14, v100, v14
	v_exp_f32_e32 v104, v104
	v_sub_f32_e32 v105, v105, v15
	v_add_f32_e32 v14, v101, v14
	v_exp_f32_e32 v105, v105
	v_sub_f32_e32 v106, v106, v15
	v_add_f32_e32 v14, v102, v14
	v_exp_f32_e32 v106, v106
	v_sub_f32_e32 v107, v107, v15
	v_add_f32_e32 v14, v103, v14
	v_exp_f32_e32 v107, v107
	v_sub_f32_e32 v108, v108, v15
	v_add_f32_e32 v14, v104, v14
	v_exp_f32_e32 v108, v108
	v_sub_f32_e32 v109, v109, v15
	v_add_f32_e32 v14, v105, v14
	v_exp_f32_e32 v109, v109
	v_sub_f32_e32 v110, v110, v15
	v_add_f32_e32 v14, v106, v14
	v_exp_f32_e32 v110, v110
	v_sub_f32_e32 v111, v111, v15
	v_add_f32_e32 v14, v107, v14
	v_exp_f32_e32 v111, v111
	v_sub_f32_e32 v80, v80, v15
	v_add_f32_e32 v14, v108, v14
	v_exp_f32_e32 v80, v80
	v_sub_f32_e32 v81, v81, v15
	v_add_f32_e32 v14, v109, v14
	v_exp_f32_e32 v81, v81
	v_sub_f32_e32 v82, v82, v15
	v_add_f32_e32 v14, v110, v14
	v_exp_f32_e32 v82, v82
	v_sub_f32_e32 v83, v83, v15
	v_add_f32_e32 v14, v111, v14
	v_exp_f32_e32 v83, v83
	v_sub_f32_e32 v84, v84, v15
	v_add_f32_e32 v14, v80, v14
	v_exp_f32_e32 v84, v84
	v_sub_f32_e32 v85, v85, v15
	v_add_f32_e32 v14, v81, v14
	v_exp_f32_e32 v85, v85
	v_sub_f32_e32 v86, v86, v15
	v_add_f32_e32 v14, v82, v14
	v_exp_f32_e32 v86, v86
	v_sub_f32_e32 v87, v87, v15
	v_add_f32_e32 v14, v83, v14
	v_exp_f32_e32 v87, v87
	v_sub_f32_e32 v88, v88, v15
	v_add_f32_e32 v14, v84, v14
	v_exp_f32_e32 v88, v88
	v_sub_f32_e32 v89, v89, v15
	v_add_f32_e32 v14, v85, v14
	v_exp_f32_e32 v89, v89
	v_sub_f32_e32 v90, v90, v15
	v_add_f32_e32 v14, v86, v14
	v_exp_f32_e32 v90, v90
	v_sub_f32_e32 v91, v91, v15
	v_add_f32_e32 v14, v87, v14
	v_exp_f32_e32 v91, v91
	v_sub_f32_e32 v92, v92, v15
	v_add_f32_e32 v14, v88, v14
	v_exp_f32_e32 v92, v92
	v_sub_f32_e32 v93, v93, v15
	v_add_f32_e32 v14, v89, v14
	v_exp_f32_e32 v93, v93
	v_sub_f32_e32 v94, v94, v15
	v_add_f32_e32 v14, v90, v14
	v_exp_f32_e32 v94, v94
	v_sub_f32_e32 v95, v95, v15
	v_add_f32_e32 v14, v91, v14
	v_exp_f32_e32 v95, v95
	v_sub_f32_e32 v0, v199, v15
	v_add_f32_e32 v14, v92, v14
	v_add_f32_e32 v14, v93, v14
	v_exp_f32_e32 v0, v0
	v_add_f32_e32 v14, v94, v14
	v_add_f32_e32 v14, v95, v14
	v_mov_b32_e32 v199, v14
	s_nop 1
	v_permlane32_swap_b32_e32 v14, v199
	v_cmp_neq_f32_e32 vcc, 1.0, v0
	s_cbranch_vccz .Lrot_s1
	v_pk_mul_f32 v[78:79], v[78:79], v[0:1] op_sel_hi:[1,0]
	v_pk_mul_f32 v[76:77], v[76:77], v[0:1] op_sel_hi:[1,0]
	v_pk_mul_f32 v[74:75], v[74:75], v[0:1] op_sel_hi:[1,0]
	v_pk_mul_f32 v[72:73], v[72:73], v[0:1] op_sel_hi:[1,0]
	v_pk_mul_f32 v[70:71], v[70:71], v[0:1] op_sel_hi:[1,0]
	v_pk_mul_f32 v[68:69], v[68:69], v[0:1] op_sel_hi:[1,0]
	v_pk_mul_f32 v[66:67], v[66:67], v[0:1] op_sel_hi:[1,0]
	v_pk_mul_f32 v[64:65], v[64:65], v[0:1] op_sel_hi:[1,0]
	v_pk_mul_f32 v[62:63], v[62:63], v[0:1] op_sel_hi:[1,0]
	v_pk_mul_f32 v[60:61], v[60:61], v[0:1] op_sel_hi:[1,0]
	v_pk_mul_f32 v[58:59], v[58:59], v[0:1] op_sel_hi:[1,0]
	v_pk_mul_f32 v[56:57], v[56:57], v[0:1] op_sel_hi:[1,0]
	v_pk_mul_f32 v[54:55], v[54:55], v[0:1] op_sel_hi:[1,0]
	v_pk_mul_f32 v[52:53], v[52:53], v[0:1] op_sel_hi:[1,0]
	v_pk_mul_f32 v[50:51], v[50:51], v[0:1] op_sel_hi:[1,0]
	v_pk_mul_f32 v[48:49], v[48:49], v[0:1] op_sel_hi:[1,0]
	v_pk_mul_f32 v[46:47], v[46:47], v[0:1] op_sel_hi:[1,0]
	v_pk_mul_f32 v[44:45], v[44:45], v[0:1] op_sel_hi:[1,0]
	v_pk_mul_f32 v[42:43], v[42:43], v[0:1] op_sel_hi:[1,0]
	v_pk_mul_f32 v[40:41], v[40:41], v[0:1] op_sel_hi:[1,0]
	v_pk_mul_f32 v[38:39], v[38:39], v[0:1] op_sel_hi:[1,0]
	v_pk_mul_f32 v[36:37], v[36:37], v[0:1] op_sel_hi:[1,0]
	v_pk_mul_f32 v[34:35], v[34:35], v[0:1] op_sel_hi:[1,0]
	v_pk_mul_f32 v[32:33], v[32:33], v[0:1] op_sel_hi:[1,0]
	v_pk_mul_f32 v[30:31], v[30:31], v[0:1] op_sel_hi:[1,0]
	v_pk_mul_f32 v[28:29], v[28:29], v[0:1] op_sel_hi:[1,0]
	v_pk_mul_f32 v[26:27], v[26:27], v[0:1] op_sel_hi:[1,0]
	v_pk_mul_f32 v[24:25], v[24:25], v[0:1] op_sel_hi:[1,0]
	v_pk_mul_f32 v[22:23], v[22:23], v[0:1] op_sel_hi:[1,0]
	v_pk_mul_f32 v[20:21], v[20:21], v[0:1] op_sel_hi:[1,0]
	v_pk_mul_f32 v[18:19], v[18:19], v[0:1] op_sel_hi:[1,0]
	v_pk_mul_f32 v[16:17], v[16:17], v[0:1] op_sel_hi:[1,0]
; DI void attn_phase(const bf16_t* __restrict__ qraw, const bf16_t* __restrict__ kbuf, const bf16_t* __restrict__ vtb, bf16_t* __restrict__ obuf,
;                    const float* __restrict__ gq, const float* __restrict__ cosT, const float* __restrict__ sinT, bf16_t* sm, int x, int j) {
;     ...
;         const bf16_t* kp = smk + r * KLS + h * 8;
;         {
;           bf16x8 ka = *(const bf16x8*)(kp), kb = *(const bf16x8*)(kp + 32 * KLS);
;           __builtin_amdgcn_sched_barrier(0);
;           if (kt + 1 < nkt) ALOAD(kt + 1);
;           __builtin_amdgcn_sched_barrier(0);
; #pragma unroll
;           for (int st = 0; st < 12; ++st) {
;             bf16x8 na = ka, nbq = kb;
;             if (st + 1 < 12) { na = *(const bf16x8*)(kp + (st + 1) * 16); nbq = *(const bf16x8*)(kp + 32 * KLS + (st + 1) * 16); }
;             sacc[0] = MFMA(ka, qf[st], sacc[0]);
;             sacc[1] = MFMA(kb, qf[st], sacc[1]);
;             ka = na; kb = nbq;
;     ...
;         l_run = l_run * alpha + rs;
;         if (__any(alpha != 1.f)) {
; #pragma unroll
;           for (int mt = 0; mt < 4; ++mt)
; #pragma unroll
;             for (int i = 0; i < 16; ++i) oacc[mt][i] *= alpha;
;         }
;         bf16x8 pf[4];
; #pragma unroll
;         for (int ks = 0; ks < 4; ++ks) {
;           u32x4 o;
;           o.x = pack_bf16(sacc[ks >> 1][8 * (ks & 1) + 0], sacc[ks >> 1][8 * (ks & 1) + 1]);
;           o.y = pack_bf16(sacc[ks >> 1][8 * (ks & 1) + 2], sacc[ks >> 1][8 * (ks & 1) + 3]);
;           o.z = pack_bf16(sacc[ks >> 1][8 * (ks & 1) + 4], sacc[ks >> 1][8 * (ks & 1) + 5]);
;           o.w = pack_bf16(sacc[ks >> 1][8 * (ks & 1) + 6], sacc[ks >> 1][8 * (ks & 1) + 7]);
;           pf[ks] = __builtin_bit_cast(bf16x8, o);
;         }
;         const bf16_t* vp = smv + r * VLS + h * 8;
;         __builtin_amdgcn_sched_barrier(0);
;         {
; #pragma unroll
;           for (int ks = 0; ks < 4; ++ks) {
;             if (ks + 1 < 4) {
; #pragma unroll
;               for (int mt = 0; mt < 4; ++mt) va[(ks + 1) & 1][mt] = *(const bf16x8*)(vp + mt * 32 * VLS + (ks + 1) * 16);
;             }
; #pragma unroll
;             for (int mt = 0; mt < 4; ++mt) oacc[mt] = MFMA(va[ks & 1][mt], pf[ks], oacc[mt]);
;             __builtin_amdgcn_sched_barrier(0);
;           }
;         }
;         }
;         if (kt + 1 < nkt) ASTORE((kt + 1) & 1);
;         __syncthreads();
.Lrot_s1:
	v_add_f32_e32 v14, v14, v199
	v_fmac_f32_e32 v14, v198, v0
	v_add_u32_e32 v197, 1, v197
	v_cvt_pk_bf16_f32 v96, v96, v97
	v_cvt_pk_bf16_f32 v97, v98, v99
	v_cvt_pk_bf16_f32 v98, v100, v101
	v_cvt_pk_bf16_f32 v99, v102, v103
	v_cvt_pk_bf16_f32 v100, v104, v105
	v_cvt_pk_bf16_f32 v101, v106, v107
	v_cvt_pk_bf16_f32 v102, v108, v109
	v_cvt_pk_bf16_f32 v103, v110, v111
	v_cvt_pk_bf16_f32 v80, v80, v81
	v_cvt_pk_bf16_f32 v81, v82, v83
	v_cvt_pk_bf16_f32 v82, v84, v85
	v_cvt_pk_bf16_f32 v83, v86, v87
	v_cvt_pk_bf16_f32 v84, v88, v89
	v_cvt_pk_bf16_f32 v85, v90, v91
	v_cvt_pk_bf16_f32 v86, v92, v93
	v_cvt_pk_bf16_f32 v87, v94, v95
	s_bitcmp1_b32 s92, 0
	s_cselect_b32 s0, 0xac00, 0
	s_cmp_eq_u32 s98, 0
	s_mov_b32 s99, 0xf400
	s_cselect_b32 s99, 0xac00, s99
	s_cmp_eq_u32 s98, 0xf400
	s_cselect_b32 s99, 0, s99
	s_add_i32 s2, s0, 0
	s_add_u32 s84, s84, 0x80
	s_addc_u32 s85, s85, 0
	s_add_u32 s54, s54, 0x6000
	v_lshl_add_u32 v0, v188, 1, s2
	s_addc_u32 s55, s55, 0
	s_add_i32 s31, s31, 64
	s_add_i32 s92, s92, 1
	s_waitcnt vmcnt(4)
	ds_write_b128 v0, v[160:163]
	s_waitcnt vmcnt(3)
	ds_write_b128 v0, v[164:167] offset:128
	s_waitcnt vmcnt(2)
	ds_write_b128 v0, v[168:171] offset:256
	v_lshl_add_u32 v0, v194, 1, s99
	s_cmp_eq_u32 s90, s31
	s_waitcnt vmcnt(1)
	ds_write_b128 v0, v[172:175] offset:25600
	s_waitcnt vmcnt(0)
	ds_write_b128 v0, v[176:179] offset:34816
	s_mov_b32 s32, s98
	s_mov_b32 s98, s99
	s_waitcnt lgkmcnt(0)
	s_barrier
	v_mov_b32_e32 v199, v15
	v_mov_b32_e32 v198, v14
.Lrot_check:
	s_sub_i32 s99, s90, 0x100
	s_cmp_gt_i32 s31, s99
	s_cbranch_scc1 .Lrot_flush
	v_lshlrev_b32_e32 v180, 1, v187
	v_add3_u32 v200, s32, v191, v180
	ds_read_b128 v[180:183], v200 offset:25600
	ds_read_b128 v[10:13], v200 offset:30208
	ds_read_b128 v[6:9], v200 offset:34816
	ds_read_b128 v[2:5], v200 offset:39424
	s_waitcnt lgkmcnt(3)
	v_mfma_f32_32x32x16_bf16 v[64:79], v[180:183], v[96:99], v[64:79]
	s_waitcnt lgkmcnt(2)
	v_mfma_f32_32x32x16_bf16 v[48:63], v[10:13], v[96:99], v[48:63]
	s_waitcnt lgkmcnt(1)
	v_mfma_f32_32x32x16_bf16 v[32:47], v[6:9], v[96:99], v[32:47]
	ds_read_b128 v[6:9], v200 offset:25632
	ds_read_b128 v[10:13], v200 offset:30240
	ds_read_b128 v[88:91], v200 offset:34848
	ds_read_b128 v[92:95], v200 offset:39456
	s_waitcnt lgkmcnt(4)
	v_mfma_f32_32x32x16_bf16 v[16:31], v[2:5], v[96:99], v[16:31]
	s_waitcnt lgkmcnt(3)
	v_mfma_f32_32x32x16_bf16 v[64:79], v[6:9], v[100:103], v[64:79]
	s_waitcnt lgkmcnt(2)
	v_mfma_f32_32x32x16_bf16 v[48:63], v[10:13], v[100:103], v[48:63]
	s_waitcnt lgkmcnt(1)
	v_mfma_f32_32x32x16_bf16 v[32:47], v[88:91], v[100:103], v[32:47]
	ds_read_b128 v[2:5], v200 offset:25664
	ds_read_b128 v[6:9], v200 offset:30272
	ds_read_b128 v[10:13], v200 offset:34880
	ds_read_b128 v[88:91], v200 offset:39488
	s_waitcnt lgkmcnt(4)
	v_mfma_f32_32x32x16_bf16 v[16:31], v[92:95], v[100:103], v[16:31]
	s_waitcnt lgkmcnt(3)
	v_mfma_f32_32x32x16_bf16 v[64:79], v[2:5], v[80:83], v[64:79]
	s_waitcnt lgkmcnt(2)
	v_mfma_f32_32x32x16_bf16 v[48:63], v[6:9], v[80:83], v[48:63]
	s_waitcnt lgkmcnt(1)
	v_mfma_f32_32x32x16_bf16 v[32:47], v[10:13], v[80:83], v[32:47]
	ds_read_b128 v[2:5], v200 offset:25696
	ds_read_b128 v[6:9], v200 offset:30304
	ds_read_b128 v[10:13], v200 offset:34912
	ds_read_b128 v[92:95], v200 offset:39520
	s_waitcnt lgkmcnt(4)
	v_mfma_f32_32x32x16_bf16 v[16:31], v[88:91], v[80:83], v[16:31]
	s_waitcnt lgkmcnt(3)
	v_mfma_f32_32x32x16_bf16 v[64:79], v[2:5], v[84:87], v[64:79]
	s_waitcnt lgkmcnt(2)
	v_mfma_f32_32x32x16_bf16 v[48:63], v[6:9], v[84:87], v[48:63]
	s_waitcnt lgkmcnt(1)
	v_mfma_f32_32x32x16_bf16 v[32:47], v[10:13], v[84:87], v[32:47]
	s_waitcnt lgkmcnt(0)
	v_mfma_f32_32x32x16_bf16 v[16:31], v[92:95], v[84:87], v[16:31]
	s_bitcmp1_b32 s92, 0
	s_cselect_b32 s2, 0, 0xac00
	s_add_i32 vcc_lo, s2, 0
	v_lshlrev_b32_e32 v180, 1, v187
	v_add3_u32 v181, vcc_lo, v195, v180
	ds_read_b128 v[2:5], v181
	ds_read_b128 v[6:9], v181 offset:12800
	v_mov_b32_e32 v0, v192
	v_mov_b32_e32 v10, v193
	s_add_u32 s2, s34, s54
	s_addc_u32 s3, s35, s55
	v_lshl_add_u64 v[12:13], v[0:1], 1, s[2:3]
	v_add_u32_e32 v14, 64, v0
	v_mov_b32_e32 v15, v1
	v_add_u32_e32 v0, 0x80, v0
	v_lshl_add_u64 v[14:15], v[14:15], 1, s[2:3]
	global_load_dwordx4 v[160:163], v[12:13], off
	global_load_dwordx4 v[164:167], v[14:15], off
	v_lshl_add_u64 v[12:13], v[0:1], 1, s[2:3]
	s_add_u32 s2, s34, s84
	v_mov_b32_e32 v11, v1
	s_addc_u32 s3, s35, s85
	v_add_u32_e32 v0, 0x101000, v10
	v_lshl_add_u64 v[14:15], v[10:11], 1, s[2:3]
	v_lshl_add_u64 v[10:11], v[0:1], 1, s[2:3]
	global_load_dwordx4 v[168:171], v[12:13], off
	global_load_dwordx4 v[172:175], v[14:15], off
	global_load_dwordx4 v[176:179], v[10:11], off
	s_waitcnt lgkmcnt(1)
	v_mfma_f32_32x32x16_bf16 v[96:111], v[2:5], v[112:115], 0
	ds_read_b128 v[2:5], v181 offset:32
	ds_read_b128 v[10:13], v181 offset:12832
	s_waitcnt lgkmcnt(2)
	v_mfma_f32_32x32x16_bf16 v[80:95], v[6:9], v[112:115], 0
	s_waitcnt lgkmcnt(1)
	v_mfma_f32_32x32x16_bf16 v[96:111], v[2:5], v[116:119], v[96:111]
	ds_read_b128 v[2:5], v181 offset:64
	ds_read_b128 v[6:9], v181 offset:12864
	s_waitcnt lgkmcnt(2)
	v_mfma_f32_32x32x16_bf16 v[80:95], v[10:13], v[116:119], v[80:95]
	s_waitcnt lgkmcnt(1)
	v_mfma_f32_32x32x16_bf16 v[96:111], v[2:5], v[120:123], v[96:111]
	ds_read_b128 v[2:5], v181 offset:96
	ds_read_b128 v[10:13], v181 offset:12896
	s_waitcnt lgkmcnt(2)
	v_mfma_f32_32x32x16_bf16 v[80:95], v[6:9], v[120:123], v[80:95]
	s_waitcnt lgkmcnt(1)
	v_mfma_f32_32x32x16_bf16 v[96:111], v[2:5], v[124:127], v[96:111]
	ds_read_b128 v[2:5], v181 offset:128
	ds_read_b128 v[6:9], v181 offset:12928
	s_waitcnt lgkmcnt(2)
; DI int crow(int i, int h) { return (i & 3) + 8 * (i >> 2) + 4 * h; }
; DI float xmax32(float v) { const u32x2 r = __builtin_amdgcn_permlane32_swap(__float_as_uint(v), __float_as_uint(v), false, false); return fmaxf(__uint_as_float(r.x), __uint_as_float(r.y)); }
; DI void attn_phase(const bf16_t* __restrict__ qraw, const bf16_t* __restrict__ kbuf, const bf16_t* __restrict__ vtb, bf16_t* __restrict__ obuf,
;                    const float* __restrict__ gq, const float* __restrict__ cosT, const float* __restrict__ sinT, bf16_t* sm, int x, int j) {
;     ...
;           for (int st = 0; st < 12; ++st) {
;             bf16x8 na = ka, nbq = kb;
;             if (st + 1 < 12) { na = *(const bf16x8*)(kp + (st + 1) * 16); nbq = *(const bf16x8*)(kp + 32 * KLS + (st + 1) * 16); }
;             sacc[0] = MFMA(ka, qf[st], sacc[0]);
;             sacc[1] = MFMA(kb, qf[st], sacc[1]);
;             ka = na; kb = nbq;
;             __builtin_amdgcn_sched_barrier(0);
;           }
;         }
;         bf16x8 va[2][4];
;         {
;           const bf16_t* vp0 = smv + r * VLS + h * 8;
; #pragma unroll
;           for (int mt = 0; mt < 4; ++mt) va[0][mt] = *(const bf16x8*)(vp0 + mt * 32 * VLS);
;         }
;         if (kt * 64 + 63 > q0) {
;           const int qpos = q0 + r;
; #pragma unroll
;           for (int mt = 0; mt < 2; ++mt)
; #pragma unroll
;             for (int i = 0; i < 16; ++i) { const int key = kt * 64 + mt * 32 + crow(i, h); if (key > qpos) sacc[mt][i] = -INFINITY; }
;         }
;         float mx = sacc[0][0];
; #pragma unroll
;         for (int mt = 0; mt < 2; ++mt)
; #pragma unroll
;           for (int i = 0; i < 16; ++i) mx = fmaxf(mx, sacc[mt][i]);
;         mx = xmax32(mx);
;         const float m_new = fmaxf(m_run, mx);
;         const float alpha = __builtin_amdgcn_exp2f(m_run - m_new);
;         m_run = m_new;
;         float rs = 0.f;
; #pragma unroll
;         for (int mt = 0; mt < 2; ++mt)
; #pragma unroll
;           for (int i = 0; i < 16; ++i) { const float pv = __builtin_amdgcn_exp2f(sacc[mt][i] - m_new); sacc[mt][i] = pv; rs += pv; }
;         rs = xsum32(rs);
;         l_run = l_run * alpha + rs;
;         if (__any(alpha != 1.f)) {
; #pragma unroll
;           for (int mt = 0; mt < 4; ++mt)
; #pragma unroll
;             for (int i = 0; i < 16; ++i) oacc[mt][i] *= alpha;
;         }
	v_mfma_f32_32x32x16_bf16 v[80:95], v[10:13], v[124:127], v[80:95]
	s_waitcnt lgkmcnt(1)
	v_mfma_f32_32x32x16_bf16 v[96:111], v[2:5], v[128:131], v[96:111]
	ds_read_b128 v[2:5], v181 offset:160
	ds_read_b128 v[10:13], v181 offset:12960
	s_waitcnt lgkmcnt(2)
	v_mfma_f32_32x32x16_bf16 v[80:95], v[6:9], v[128:131], v[80:95]
	s_waitcnt lgkmcnt(1)
	v_mfma_f32_32x32x16_bf16 v[96:111], v[2:5], v[132:135], v[96:111]
	ds_read_b128 v[2:5], v181 offset:192
	ds_read_b128 v[6:9], v181 offset:12992
	s_waitcnt lgkmcnt(2)
	v_mfma_f32_32x32x16_bf16 v[80:95], v[10:13], v[132:135], v[80:95]
	s_waitcnt lgkmcnt(1)
	v_mfma_f32_32x32x16_bf16 v[96:111], v[2:5], v[136:139], v[96:111]
	ds_read_b128 v[2:5], v181 offset:224
	ds_read_b128 v[10:13], v181 offset:13024
	s_waitcnt lgkmcnt(2)
	v_mfma_f32_32x32x16_bf16 v[80:95], v[6:9], v[136:139], v[80:95]
	s_waitcnt lgkmcnt(1)
	v_mfma_f32_32x32x16_bf16 v[96:111], v[2:5], v[140:143], v[96:111]
	ds_read_b128 v[2:5], v181 offset:256
	ds_read_b128 v[6:9], v181 offset:13056
	s_waitcnt lgkmcnt(2)
	v_mfma_f32_32x32x16_bf16 v[80:95], v[10:13], v[140:143], v[80:95]
	s_waitcnt lgkmcnt(1)
	v_mfma_f32_32x32x16_bf16 v[96:111], v[2:5], v[148:151], v[96:111]
	ds_read_b128 v[2:5], v181 offset:288
	ds_read_b128 v[10:13], v181 offset:13088
	s_waitcnt lgkmcnt(2)
	v_mfma_f32_32x32x16_bf16 v[80:95], v[6:9], v[148:151], v[80:95]
	s_waitcnt lgkmcnt(1)
	v_mfma_f32_32x32x16_bf16 v[96:111], v[2:5], v[156:159], v[96:111]
	ds_read_b128 v[2:5], v181 offset:320
	ds_read_b128 v[6:9], v181 offset:13120
	s_waitcnt lgkmcnt(2)
	v_mfma_f32_32x32x16_bf16 v[80:95], v[10:13], v[156:159], v[80:95]
	s_waitcnt lgkmcnt(1)
	v_mfma_f32_32x32x16_bf16 v[96:111], v[2:5], v[144:147], v[96:111]
	ds_read_b128 v[202:205], v181 offset:352
	ds_read_b128 v[2:5], v181 offset:13152
	s_waitcnt lgkmcnt(2)
	v_mfma_f32_32x32x16_bf16 v[80:95], v[6:9], v[144:147], v[80:95]
	s_waitcnt lgkmcnt(0)
	v_mfma_f32_32x32x16_bf16 v[80:95], v[2:5], v[152:155], v[80:95]
	v_mfma_f32_32x32x16_bf16 v[96:111], v[202:205], v[152:155], v[96:111]
	s_nop 7
	s_nop 4
	s_nop 2
	v_max_f32_e32 v0, v97, v97
	v_max_f32_e32 v14, v96, v96
	v_max_f32_e32 v0, v14, v0
	v_max3_f32 v0, v0, v98, v99
	v_max3_f32 v0, v0, v100, v101
	v_max3_f32 v0, v0, v102, v103
	v_max3_f32 v0, v0, v104, v105
	v_max3_f32 v0, v0, v106, v107
	v_max3_f32 v0, v0, v108, v109
	v_max3_f32 v0, v0, v110, v111
	v_max3_f32 v0, v0, v80, v81
	v_max3_f32 v0, v0, v82, v83
	v_max3_f32 v0, v0, v84, v85
	v_max3_f32 v0, v0, v86, v87
	v_max3_f32 v0, v0, v88, v89
	v_max3_f32 v0, v0, v90, v91
	v_max3_f32 v0, v0, v92, v93
	v_max3_f32 v0, v0, v94, v95
	v_mov_b32_e32 v14, v0
	s_nop 1
	v_permlane32_swap_b32_e32 v0, v14
	v_max3_f32 v15, v199, v0, v14
	v_sub_f32_e32 v14, v96, v15
	v_exp_f32_e32 v96, v14
	v_sub_f32_e32 v14, v97, v15
	v_exp_f32_e32 v97, v14
	v_sub_f32_e32 v14, v98, v15
	v_exp_f32_e32 v98, v14
	v_sub_f32_e32 v14, v99, v15
	v_exp_f32_e32 v99, v14
	v_sub_f32_e32 v100, v100, v15
	v_add_f32_e32 v14, 0, v96
	v_exp_f32_e32 v100, v100
	v_sub_f32_e32 v101, v101, v15
	v_add_f32_e32 v14, v97, v14
	v_exp_f32_e32 v101, v101
	v_sub_f32_e32 v102, v102, v15
	v_add_f32_e32 v14, v98, v14
	v_exp_f32_e32 v102, v102
	v_sub_f32_e32 v103, v103, v15
	v_add_f32_e32 v14, v99, v14
	v_exp_f32_e32 v103, v103
	v_sub_f32_e32 v104, v104, v15
	v_add_f32_e32 v14, v100, v14
	v_exp_f32_e32 v104, v104
	v_sub_f32_e32 v105, v105, v15
	v_add_f32_e32 v14, v101, v14
	v_exp_f32_e32 v105, v105
	v_sub_f32_e32 v106, v106, v15
	v_add_f32_e32 v14, v102, v14
	v_exp_f32_e32 v106, v106
	v_sub_f32_e32 v107, v107, v15
	v_add_f32_e32 v14, v103, v14
	v_exp_f32_e32 v107, v107
	v_sub_f32_e32 v108, v108, v15
	v_add_f32_e32 v14, v104, v14
	v_exp_f32_e32 v108, v108
	v_sub_f32_e32 v109, v109, v15
	v_add_f32_e32 v14, v105, v14
	v_exp_f32_e32 v109, v109
	v_sub_f32_e32 v110, v110, v15
	v_add_f32_e32 v14, v106, v14
	v_exp_f32_e32 v110, v110
	v_sub_f32_e32 v111, v111, v15
	v_add_f32_e32 v14, v107, v14
	v_exp_f32_e32 v111, v111
	v_sub_f32_e32 v80, v80, v15
	v_add_f32_e32 v14, v108, v14
	v_exp_f32_e32 v80, v80
	v_sub_f32_e32 v81, v81, v15
	v_add_f32_e32 v14, v109, v14
	v_exp_f32_e32 v81, v81
	v_sub_f32_e32 v82, v82, v15
	v_add_f32_e32 v14, v110, v14
	v_exp_f32_e32 v82, v82
	v_sub_f32_e32 v83, v83, v15
	v_add_f32_e32 v14, v111, v14
	v_exp_f32_e32 v83, v83
	v_sub_f32_e32 v84, v84, v15
	v_add_f32_e32 v14, v80, v14
	v_exp_f32_e32 v84, v84
	v_sub_f32_e32 v85, v85, v15
	v_add_f32_e32 v14, v81, v14
	v_exp_f32_e32 v85, v85
	v_sub_f32_e32 v86, v86, v15
	v_add_f32_e32 v14, v82, v14
	v_exp_f32_e32 v86, v86
	v_sub_f32_e32 v87, v87, v15
	v_add_f32_e32 v14, v83, v14
	v_exp_f32_e32 v87, v87
	v_sub_f32_e32 v88, v88, v15
	v_add_f32_e32 v14, v84, v14
	v_exp_f32_e32 v88, v88
	v_sub_f32_e32 v89, v89, v15
	v_add_f32_e32 v14, v85, v14
	v_exp_f32_e32 v89, v89
	v_sub_f32_e32 v90, v90, v15
	v_add_f32_e32 v14, v86, v14
	v_exp_f32_e32 v90, v90
	v_sub_f32_e32 v91, v91, v15
	v_add_f32_e32 v14, v87, v14
	v_exp_f32_e32 v91, v91
	v_sub_f32_e32 v92, v92, v15
	v_add_f32_e32 v14, v88, v14
	v_exp_f32_e32 v92, v92
	v_sub_f32_e32 v93, v93, v15
	v_add_f32_e32 v14, v89, v14
	v_exp_f32_e32 v93, v93
	v_sub_f32_e32 v94, v94, v15
	v_add_f32_e32 v14, v90, v14
	v_exp_f32_e32 v94, v94
	v_sub_f32_e32 v95, v95, v15
	v_add_f32_e32 v14, v91, v14
	v_exp_f32_e32 v95, v95
	v_sub_f32_e32 v0, v199, v15
	v_add_f32_e32 v14, v92, v14
	v_add_f32_e32 v14, v93, v14
	v_exp_f32_e32 v0, v0
	v_add_f32_e32 v14, v94, v14
	v_add_f32_e32 v14, v95, v14
	v_mov_b32_e32 v199, v14
	s_nop 1
	v_permlane32_swap_b32_e32 v14, v199
	v_cmp_neq_f32_e32 vcc, 1.0, v0
	s_cbranch_vccz .Lrot_s2
; DI unsigned pack_bf16(float lo, float hi) { f32x2 v = {lo, hi}; bf16v2 b = __builtin_convertvector(v, bf16v2); return __builtin_bit_cast(unsigned, b); }
; #define MFMA(a, b, c) __builtin_amdgcn_mfma_f32_32x32x16_bf16((a), (b), (c), 0, 0, 0)
; DI void attn_phase(const bf16_t* __restrict__ qraw, const bf16_t* __restrict__ kbuf, const bf16_t* __restrict__ vtb, bf16_t* __restrict__ obuf,
;                    const float* __restrict__ gq, const float* __restrict__ cosT, const float* __restrict__ sinT, bf16_t* sm, int x, int j) {
;     ...
;         if (__any(alpha != 1.f)) {
; #pragma unroll
;           for (int mt = 0; mt < 4; ++mt)
; #pragma unroll
;             for (int i = 0; i < 16; ++i) oacc[mt][i] *= alpha;
;         }
;         bf16x8 pf[4];
; #pragma unroll
;         for (int ks = 0; ks < 4; ++ks) {
;           u32x4 o;
;           o.x = pack_bf16(sacc[ks >> 1][8 * (ks & 1) + 0], sacc[ks >> 1][8 * (ks & 1) + 1]);
;           o.y = pack_bf16(sacc[ks >> 1][8 * (ks & 1) + 2], sacc[ks >> 1][8 * (ks & 1) + 3]);
;           o.z = pack_bf16(sacc[ks >> 1][8 * (ks & 1) + 4], sacc[ks >> 1][8 * (ks & 1) + 5]);
;           o.w = pack_bf16(sacc[ks >> 1][8 * (ks & 1) + 6], sacc[ks >> 1][8 * (ks & 1) + 7]);
;           pf[ks] = __builtin_bit_cast(bf16x8, o);
;         }
;         const bf16_t* vp = smv + r * VLS + h * 8;
;         __builtin_amdgcn_sched_barrier(0);
;         {
; #pragma unroll
;           for (int ks = 0; ks < 4; ++ks) {
;             if (ks + 1 < 4) {
; #pragma unroll
;               for (int mt = 0; mt < 4; ++mt) va[(ks + 1) & 1][mt] = *(const bf16x8*)(vp + mt * 32 * VLS + (ks + 1) * 16);
;             }
; #pragma unroll
;             for (int mt = 0; mt < 4; ++mt) oacc[mt] = MFMA(va[ks & 1][mt], pf[ks], oacc[mt]);
;             __builtin_amdgcn_sched_barrier(0);
;           }
;         }
;         }
;         if (kt + 1 < nkt) ASTORE((kt + 1) & 1);
;         __syncthreads();
	v_pk_mul_f32 v[78:79], v[78:79], v[0:1] op_sel_hi:[1,0]
	v_pk_mul_f32 v[76:77], v[76:77], v[0:1] op_sel_hi:[1,0]
	v_pk_mul_f32 v[74:75], v[74:75], v[0:1] op_sel_hi:[1,0]
	v_pk_mul_f32 v[72:73], v[72:73], v[0:1] op_sel_hi:[1,0]
	v_pk_mul_f32 v[70:71], v[70:71], v[0:1] op_sel_hi:[1,0]
	v_pk_mul_f32 v[68:69], v[68:69], v[0:1] op_sel_hi:[1,0]
	v_pk_mul_f32 v[66:67], v[66:67], v[0:1] op_sel_hi:[1,0]
	v_pk_mul_f32 v[64:65], v[64:65], v[0:1] op_sel_hi:[1,0]
	v_pk_mul_f32 v[62:63], v[62:63], v[0:1] op_sel_hi:[1,0]
	v_pk_mul_f32 v[60:61], v[60:61], v[0:1] op_sel_hi:[1,0]
	v_pk_mul_f32 v[58:59], v[58:59], v[0:1] op_sel_hi:[1,0]
	v_pk_mul_f32 v[56:57], v[56:57], v[0:1] op_sel_hi:[1,0]
	v_pk_mul_f32 v[54:55], v[54:55], v[0:1] op_sel_hi:[1,0]
	v_pk_mul_f32 v[52:53], v[52:53], v[0:1] op_sel_hi:[1,0]
	v_pk_mul_f32 v[50:51], v[50:51], v[0:1] op_sel_hi:[1,0]
	v_pk_mul_f32 v[48:49], v[48:49], v[0:1] op_sel_hi:[1,0]
	v_pk_mul_f32 v[46:47], v[46:47], v[0:1] op_sel_hi:[1,0]
	v_pk_mul_f32 v[44:45], v[44:45], v[0:1] op_sel_hi:[1,0]
	v_pk_mul_f32 v[42:43], v[42:43], v[0:1] op_sel_hi:[1,0]
	v_pk_mul_f32 v[40:41], v[40:41], v[0:1] op_sel_hi:[1,0]
	v_pk_mul_f32 v[38:39], v[38:39], v[0:1] op_sel_hi:[1,0]
	v_pk_mul_f32 v[36:37], v[36:37], v[0:1] op_sel_hi:[1,0]
	v_pk_mul_f32 v[34:35], v[34:35], v[0:1] op_sel_hi:[1,0]
	v_pk_mul_f32 v[32:33], v[32:33], v[0:1] op_sel_hi:[1,0]
	v_pk_mul_f32 v[30:31], v[30:31], v[0:1] op_sel_hi:[1,0]
	v_pk_mul_f32 v[28:29], v[28:29], v[0:1] op_sel_hi:[1,0]
	v_pk_mul_f32 v[26:27], v[26:27], v[0:1] op_sel_hi:[1,0]
	v_pk_mul_f32 v[24:25], v[24:25], v[0:1] op_sel_hi:[1,0]
	v_pk_mul_f32 v[22:23], v[22:23], v[0:1] op_sel_hi:[1,0]
	v_pk_mul_f32 v[20:21], v[20:21], v[0:1] op_sel_hi:[1,0]
	v_pk_mul_f32 v[18:19], v[18:19], v[0:1] op_sel_hi:[1,0]
	v_pk_mul_f32 v[16:17], v[16:17], v[0:1] op_sel_hi:[1,0]
.Lrot_s2:
	v_add_f32_e32 v14, v14, v199
	v_fmac_f32_e32 v14, v198, v0
	v_add_u32_e32 v197, 1, v197
	v_cvt_pk_bf16_f32 v96, v96, v97
	v_cvt_pk_bf16_f32 v97, v98, v99
	v_cvt_pk_bf16_f32 v98, v100, v101
	v_cvt_pk_bf16_f32 v99, v102, v103
	v_cvt_pk_bf16_f32 v100, v104, v105
	v_cvt_pk_bf16_f32 v101, v106, v107
	v_cvt_pk_bf16_f32 v102, v108, v109
	v_cvt_pk_bf16_f32 v103, v110, v111
	v_cvt_pk_bf16_f32 v80, v80, v81
	v_cvt_pk_bf16_f32 v81, v82, v83
	v_cvt_pk_bf16_f32 v82, v84, v85
	v_cvt_pk_bf16_f32 v83, v86, v87
	v_cvt_pk_bf16_f32 v84, v88, v89
	v_cvt_pk_bf16_f32 v85, v90, v91
	v_cvt_pk_bf16_f32 v86, v92, v93
	v_cvt_pk_bf16_f32 v87, v94, v95
	s_bitcmp1_b32 s92, 0
	s_cselect_b32 s0, 0xac00, 0
	s_cmp_eq_u32 s98, 0
	s_mov_b32 s99, 0xf400
	s_cselect_b32 s99, 0xac00, s99
	s_cmp_eq_u32 s98, 0xf400
	s_cselect_b32 s99, 0, s99
	s_add_i32 s2, s0, 0
	s_add_u32 s84, s84, 0x80
	s_addc_u32 s85, s85, 0
	s_add_u32 s54, s54, 0x6000
	v_lshl_add_u32 v0, v188, 1, s2
	s_addc_u32 s55, s55, 0
	s_add_i32 s31, s31, 64
	s_add_i32 s92, s92, 1
	s_waitcnt vmcnt(4)
	ds_write_b128 v0, v[160:163]
	s_waitcnt vmcnt(3)
	ds_write_b128 v0, v[164:167] offset:128
	s_waitcnt vmcnt(2)
	ds_write_b128 v0, v[168:171] offset:256
	v_lshl_add_u32 v0, v194, 1, s99
	s_cmp_eq_u32 s90, s31
	s_waitcnt vmcnt(1)
	ds_write_b128 v0, v[172:175] offset:25600
	s_waitcnt vmcnt(0)
	ds_write_b128 v0, v[176:179] offset:34816
	s_mov_b32 s32, s98
	s_mov_b32 s98, s99
	s_waitcnt lgkmcnt(0)
	s_barrier
	v_mov_b32_e32 v199, v15
	v_mov_b32_e32 v198, v14
	s_branch .Lrot_check
.Lrot_flush:
	v_lshlrev_b32_e32 v180, 1, v187
	v_add3_u32 v200, s32, v191, v180
	ds_read_b128 v[180:183], v200 offset:25600
	ds_read_b128 v[10:13], v200 offset:30208
	ds_read_b128 v[6:9], v200 offset:34816
	ds_read_b128 v[2:5], v200 offset:39424
	s_waitcnt lgkmcnt(3)
	v_mfma_f32_32x32x16_bf16 v[64:79], v[180:183], v[96:99], v[64:79]
	s_waitcnt lgkmcnt(2)
	v_mfma_f32_32x32x16_bf16 v[48:63], v[10:13], v[96:99], v[48:63]
	s_waitcnt lgkmcnt(1)
	v_mfma_f32_32x32x16_bf16 v[32:47], v[6:9], v[96:99], v[32:47]
	ds_read_b128 v[6:9], v200 offset:25632
	ds_read_b128 v[10:13], v200 offset:30240
	ds_read_b128 v[88:91], v200 offset:34848
	ds_read_b128 v[92:95], v200 offset:39456
	s_waitcnt lgkmcnt(4)
	v_mfma_f32_32x32x16_bf16 v[16:31], v[2:5], v[96:99], v[16:31]
	s_waitcnt lgkmcnt(3)
	v_mfma_f32_32x32x16_bf16 v[64:79], v[6:9], v[100:103], v[64:79]
	s_waitcnt lgkmcnt(2)
	v_mfma_f32_32x32x16_bf16 v[48:63], v[10:13], v[100:103], v[48:63]
	s_waitcnt lgkmcnt(1)
	v_mfma_f32_32x32x16_bf16 v[32:47], v[88:91], v[100:103], v[32:47]
	ds_read_b128 v[2:5], v200 offset:25664
	ds_read_b128 v[6:9], v200 offset:30272
	ds_read_b128 v[10:13], v200 offset:34880
	ds_read_b128 v[88:91], v200 offset:39488
	s_waitcnt lgkmcnt(4)
	v_mfma_f32_32x32x16_bf16 v[16:31], v[92:95], v[100:103], v[16:31]
	s_waitcnt lgkmcnt(3)
	v_mfma_f32_32x32x16_bf16 v[64:79], v[2:5], v[80:83], v[64:79]
	s_waitcnt lgkmcnt(2)
	v_mfma_f32_32x32x16_bf16 v[48:63], v[6:9], v[80:83], v[48:63]
	s_waitcnt lgkmcnt(1)
	v_mfma_f32_32x32x16_bf16 v[32:47], v[10:13], v[80:83], v[32:47]
	ds_read_b128 v[2:5], v200 offset:25696
	ds_read_b128 v[6:9], v200 offset:30304
	ds_read_b128 v[10:13], v200 offset:34912
	ds_read_b128 v[92:95], v200 offset:39520
	s_waitcnt lgkmcnt(4)
	v_mfma_f32_32x32x16_bf16 v[16:31], v[88:91], v[80:83], v[16:31]
	s_waitcnt lgkmcnt(3)
	v_mfma_f32_32x32x16_bf16 v[64:79], v[2:5], v[84:87], v[64:79]
	s_waitcnt lgkmcnt(2)
	v_mfma_f32_32x32x16_bf16 v[48:63], v[6:9], v[84:87], v[48:63]
	s_waitcnt lgkmcnt(1)
	v_mfma_f32_32x32x16_bf16 v[32:47], v[10:13], v[84:87], v[32:47]
	s_waitcnt lgkmcnt(0)
	v_mfma_f32_32x32x16_bf16 v[16:31], v[92:95], v[84:87], v[16:31]
	s_branch .Lrot_resume
; DI int crow(int i, int h) { return (i & 3) + 8 * (i >> 2) + 4 * h; }
; #define MFMA(a, b, c) __builtin_amdgcn_mfma_f32_32x32x16_bf16((a), (b), (c), 0, 0, 0)
; DI void attn_phase(const bf16_t* __restrict__ qraw, const bf16_t* __restrict__ kbuf, const bf16_t* __restrict__ vtb, bf16_t* __restrict__ obuf,
;                    const float* __restrict__ gq, const float* __restrict__ cosT, const float* __restrict__ sinT, bf16_t* sm, int x, int j) {
;     ...
;         if (act_tile) {
;         f32x16 sacc[2];
; #pragma unroll
;         for (int mt = 0; mt < 2; ++mt)
; #pragma unroll
;           for (int i = 0; i < 16; ++i) sacc[mt][i] = 0.f;
;         const bf16_t* kp = smk + r * KLS + h * 8;
;         {
;           bf16x8 ka = *(const bf16x8*)(kp), kb = *(const bf16x8*)(kp + 32 * KLS);
;           __builtin_amdgcn_sched_barrier(0);
;           if (kt + 1 < nkt) ALOAD(kt + 1);
;           __builtin_amdgcn_sched_barrier(0);
; #pragma unroll
;           for (int st = 0; st < 12; ++st) {
;             bf16x8 na = ka, nbq = kb;
;             if (st + 1 < 12) { na = *(const bf16x8*)(kp + (st + 1) * 16); nbq = *(const bf16x8*)(kp + 32 * KLS + (st + 1) * 16); }
;             sacc[0] = MFMA(ka, qf[st], sacc[0]);
;             sacc[1] = MFMA(kb, qf[st], sacc[1]);
;             ka = na; kb = nbq;
;             __builtin_amdgcn_sched_barrier(0);
;           }
;         }
;         bf16x8 va[2][4];
;         {
;           const bf16_t* vp0 = smv + r * VLS + h * 8;
; #pragma unroll
;           for (int mt = 0; mt < 4; ++mt) va[0][mt] = *(const bf16x8*)(vp0 + mt * 32 * VLS);
;         }
;         if (kt * 64 + 63 > q0) {
;           const int qpos = q0 + r;
; #pragma unroll
;           for (int mt = 0; mt < 2; ++mt)
; #pragma unroll
;             for (int i = 0; i < 16; ++i) { const int key = kt * 64 + mt * 32 + crow(i, h); if (key > qpos) sacc[mt][i] = -INFINITY; }
;         }
.LBB0_1292:
	v_cmp_le_i32_e32 vcc, s90, v196
	s_and_saveexec_b64 s[0:1], vcc
	s_cbranch_execz .LBB0_1279
	v_lshlrev_b32_e32 v0, 1, v187
	v_add3_u32 v160, s2, v195, v0
	ds_read_b128 v[2:5], v160
	ds_read_b128 v[6:9], v160 offset:12800
	s_waitcnt lgkmcnt(1)
	v_mfma_f32_32x32x16_bf16 v[96:111], v[2:5], v[112:115], 0
	ds_read_b128 v[2:5], v160 offset:32
	ds_read_b128 v[10:13], v160 offset:12832
	s_waitcnt lgkmcnt(2)
	v_mfma_f32_32x32x16_bf16 v[80:95], v[6:9], v[112:115], 0
	s_waitcnt lgkmcnt(1)
	v_mfma_f32_32x32x16_bf16 v[96:111], v[2:5], v[116:119], v[96:111]
	ds_read_b128 v[2:5], v160 offset:64
	ds_read_b128 v[6:9], v160 offset:12864
	s_waitcnt lgkmcnt(2)
	v_mfma_f32_32x32x16_bf16 v[80:95], v[10:13], v[116:119], v[80:95]
	s_waitcnt lgkmcnt(1)
	v_mfma_f32_32x32x16_bf16 v[96:111], v[2:5], v[120:123], v[96:111]
	ds_read_b128 v[2:5], v160 offset:96
	ds_read_b128 v[10:13], v160 offset:12896
	s_waitcnt lgkmcnt(2)
	v_mfma_f32_32x32x16_bf16 v[80:95], v[6:9], v[120:123], v[80:95]
	s_waitcnt lgkmcnt(1)
	v_mfma_f32_32x32x16_bf16 v[96:111], v[2:5], v[124:127], v[96:111]
	ds_read_b128 v[2:5], v160 offset:128
	ds_read_b128 v[6:9], v160 offset:12928
	s_waitcnt lgkmcnt(2)
	v_mfma_f32_32x32x16_bf16 v[80:95], v[10:13], v[124:127], v[80:95]
	s_waitcnt lgkmcnt(1)
	v_mfma_f32_32x32x16_bf16 v[96:111], v[2:5], v[128:131], v[96:111]
	ds_read_b128 v[2:5], v160 offset:160
	ds_read_b128 v[10:13], v160 offset:12960
	s_waitcnt lgkmcnt(2)
	v_mfma_f32_32x32x16_bf16 v[80:95], v[6:9], v[128:131], v[80:95]
	s_waitcnt lgkmcnt(1)
	v_mfma_f32_32x32x16_bf16 v[96:111], v[2:5], v[132:135], v[96:111]
	ds_read_b128 v[2:5], v160 offset:192
	ds_read_b128 v[6:9], v160 offset:12992
	s_waitcnt lgkmcnt(2)
	v_mfma_f32_32x32x16_bf16 v[80:95], v[10:13], v[132:135], v[80:95]
	s_waitcnt lgkmcnt(1)
	v_mfma_f32_32x32x16_bf16 v[96:111], v[2:5], v[136:139], v[96:111]
	ds_read_b128 v[2:5], v160 offset:224
	ds_read_b128 v[10:13], v160 offset:13024
	s_waitcnt lgkmcnt(2)
	v_mfma_f32_32x32x16_bf16 v[80:95], v[6:9], v[136:139], v[80:95]
	s_waitcnt lgkmcnt(1)
	v_mfma_f32_32x32x16_bf16 v[96:111], v[2:5], v[140:143], v[96:111]
	ds_read_b128 v[2:5], v160 offset:256
	ds_read_b128 v[6:9], v160 offset:13056
	s_waitcnt lgkmcnt(2)
	v_mfma_f32_32x32x16_bf16 v[80:95], v[10:13], v[140:143], v[80:95]
	s_waitcnt lgkmcnt(1)
	v_mfma_f32_32x32x16_bf16 v[96:111], v[2:5], v[148:151], v[96:111]
	ds_read_b128 v[2:5], v160 offset:288
	ds_read_b128 v[10:13], v160 offset:13088
	s_waitcnt lgkmcnt(2)
	v_mfma_f32_32x32x16_bf16 v[80:95], v[6:9], v[148:151], v[80:95]
	s_waitcnt lgkmcnt(1)
	v_mfma_f32_32x32x16_bf16 v[96:111], v[2:5], v[156:159], v[96:111]
	ds_read_b128 v[2:5], v160 offset:320
	ds_read_b128 v[6:9], v160 offset:13120
	s_waitcnt lgkmcnt(2)
	v_mfma_f32_32x32x16_bf16 v[80:95], v[10:13], v[156:159], v[80:95]
	s_waitcnt lgkmcnt(1)
	v_mfma_f32_32x32x16_bf16 v[96:111], v[2:5], v[144:147], v[96:111]
	ds_read_b128 v[118:121], v160 offset:352
	ds_read_b128 v[2:5], v160 offset:13152
	s_waitcnt lgkmcnt(2)
	v_mfma_f32_32x32x16_bf16 v[80:95], v[6:9], v[144:147], v[80:95]
	s_waitcnt lgkmcnt(0)
	v_mfma_f32_32x32x16_bf16 v[80:95], v[2:5], v[152:155], v[80:95]
	v_add3_u32 v116, s98, v191, v0
	v_mfma_f32_32x32x16_bf16 v[96:111], v[118:121], v[152:155], v[96:111]
	ds_read_b128 v[112:115], v116 offset:25600
	ds_read_b128 v[10:13], v116 offset:30208
	ds_read_b128 v[6:9], v116 offset:34816
	ds_read_b128 v[2:5], v116 offset:39424
	s_or_b32 s2, s90, 63
	v_cmp_gt_i32_e32 vcc, s2, v186
	s_and_saveexec_b64 s[54:55], vcc
	s_cbranch_execz .LBB0_1295
	v_or_b32_e32 v0, s90, v189
	v_cmp_gt_i32_e32 vcc, v0, v190
	s_nop 1
	v_cndmask_b32_e32 v117, v96, v220, vcc
	v_cmp_lt_i32_e32 vcc, v0, v190
	s_nop 1
	v_cndmask_b32_e32 v96, v117, v96, vcc
	v_or_b32_e32 v117, 2, v0
	v_cndmask_b32_e32 v97, v220, v97, vcc
	v_cmp_le_i32_e32 vcc, v117, v190
	v_or_b32_e32 v117, 3, v0
	s_nop 0
	v_cndmask_b32_e32 v98, v220, v98, vcc
	v_cmp_le_i32_e32 vcc, v117, v190
	v_or_b32_e32 v117, 8, v0
	s_nop 0
	v_cndmask_b32_e32 v99, v220, v99, vcc
	v_cmp_le_i32_e32 vcc, v117, v190
	v_or_b32_e32 v117, 9, v0
	s_nop 0
	v_cndmask_b32_e32 v100, v220, v100, vcc
	v_cmp_le_i32_e32 vcc, v117, v190
	v_or_b32_e32 v117, 10, v0
	s_nop 0
	v_cndmask_b32_e32 v101, v220, v101, vcc
	v_cmp_le_i32_e32 vcc, v117, v190
	v_or_b32_e32 v117, 11, v0
	s_nop 0
	v_cndmask_b32_e32 v102, v220, v102, vcc
	v_cmp_le_i32_e32 vcc, v117, v190
	v_or_b32_e32 v117, 16, v0
	s_nop 0
	v_cndmask_b32_e32 v103, v220, v103, vcc
	v_cmp_le_i32_e32 vcc, v117, v190
	v_or_b32_e32 v117, 17, v0
	s_nop 0
	v_cndmask_b32_e32 v104, v220, v104, vcc
	v_cmp_le_i32_e32 vcc, v117, v190
	v_or_b32_e32 v117, 18, v0
	s_nop 0
	v_cndmask_b32_e32 v105, v220, v105, vcc
	v_cmp_le_i32_e32 vcc, v117, v190
	v_or_b32_e32 v117, 19, v0
	s_nop 0
	v_cndmask_b32_e32 v106, v220, v106, vcc
	v_cmp_le_i32_e32 vcc, v117, v190
	v_or_b32_e32 v117, 24, v0
	s_nop 0
	v_cndmask_b32_e32 v107, v220, v107, vcc
	v_cmp_le_i32_e32 vcc, v117, v190
	v_or_b32_e32 v117, 25, v0
	s_nop 0
	v_cndmask_b32_e32 v108, v220, v108, vcc
	v_cmp_le_i32_e32 vcc, v117, v190
	v_or_b32_e32 v117, 26, v0
	s_nop 0
	v_cndmask_b32_e32 v109, v220, v109, vcc
	v_cmp_le_i32_e32 vcc, v117, v190
	v_or_b32_e32 v117, 27, v0
	s_nop 0
	v_cndmask_b32_e32 v110, v220, v110, vcc
	v_cmp_le_i32_e32 vcc, v117, v190
	v_or_b32_e32 v117, 32, v0
	s_nop 0
	v_cndmask_b32_e32 v111, v220, v111, vcc
	v_cmp_le_i32_e32 vcc, v117, v190
	v_or_b32_e32 v117, 33, v0
	s_nop 0
	v_cndmask_b32_e32 v80, v220, v80, vcc
	v_cmp_le_i32_e32 vcc, v117, v190
	v_or_b32_e32 v117, 34, v0
	s_nop 0
	v_cndmask_b32_e32 v81, v220, v81, vcc
	v_cmp_le_i32_e32 vcc, v117, v190
	v_or_b32_e32 v117, 35, v0
	s_nop 0
	v_cndmask_b32_e32 v82, v220, v82, vcc
	v_cmp_le_i32_e32 vcc, v117, v190
	v_or_b32_e32 v117, 40, v0
	s_nop 0
	v_cndmask_b32_e32 v83, v220, v83, vcc
	v_cmp_le_i32_e32 vcc, v117, v190
	v_or_b32_e32 v117, 41, v0
	s_nop 0
	v_cndmask_b32_e32 v84, v220, v84, vcc
	v_cmp_le_i32_e32 vcc, v117, v190
	v_or_b32_e32 v117, 42, v0
	s_nop 0
	v_cndmask_b32_e32 v85, v220, v85, vcc
	v_cmp_le_i32_e32 vcc, v117, v190
	v_or_b32_e32 v117, 43, v0
	s_nop 0
	v_cndmask_b32_e32 v86, v220, v86, vcc
	v_cmp_le_i32_e32 vcc, v117, v190
	v_or_b32_e32 v117, 48, v0
	s_nop 0
	v_cndmask_b32_e32 v87, v220, v87, vcc
	v_cmp_le_i32_e32 vcc, v117, v190
	v_or_b32_e32 v117, 49, v0
	s_nop 0
	v_cndmask_b32_e32 v88, v220, v88, vcc
	v_cmp_le_i32_e32 vcc, v117, v190
	v_or_b32_e32 v117, 50, v0
	s_nop 0
	v_cndmask_b32_e32 v89, v220, v89, vcc
	v_cmp_le_i32_e32 vcc, v117, v190
	v_or_b32_e32 v117, 51, v0
	s_nop 0
	v_cndmask_b32_e32 v90, v220, v90, vcc
	v_cmp_le_i32_e32 vcc, v117, v190
	v_or_b32_e32 v117, 56, v0
	s_nop 0
	v_cndmask_b32_e32 v91, v220, v91, vcc
	v_cmp_le_i32_e32 vcc, v117, v190
	v_or_b32_e32 v117, 57, v0
	s_nop 0
	v_cndmask_b32_e32 v92, v220, v92, vcc
	v_cmp_le_i32_e32 vcc, v117, v190
	v_or_b32_e32 v117, 58, v0
	v_or_b32_e32 v0, 59, v0
	v_cndmask_b32_e32 v93, v220, v93, vcc
	v_cmp_le_i32_e32 vcc, v117, v190
	s_nop 1
	v_cndmask_b32_e32 v94, v220, v94, vcc
	v_cmp_le_i32_e32 vcc, v0, v190
	s_nop 1
	v_cndmask_b32_e32 v95, v220, v95, vcc
